# speedup vs baseline: 1.0176x; 1.0021x over previous
.LBB0_932:
	v_lshl_add_u32 v144, s71, 8, v133
	s_lshl_b32 s12, s10, 8
	v_ashrrev_i32_e32 v145, 31, v144
	s_ashr_i32 s13, s12, 31
	v_lshlrev_b64 v[152:153], 11, v[144:145]
	v_mov_b32_e32 v143, s13
	v_or_b32_e32 v142, s12, v132
	v_lshl_add_u64 v[152:153], s[62:63], 0, v[152:153]
	v_lshl_add_u64 v[152:153], v[142:143], 1, v[152:153]
	global_load_dwordx2 v[164:165], v[152:153], off
	global_load_dwordx2 v[166:167], v[152:153], off offset:32
	global_load_dwordx2 v[168:169], v[152:153], off offset:256
	global_load_dwordx2 v[170:171], v[152:153], off offset:288
	v_add_co_u32_e32 v230, vcc, 0x8000, v152
	s_nop 1
	v_addc_co_u32_e32 v231, vcc, 0, v153, vcc
	global_load_dwordx2 v[172:173], v[230:231], off
	global_load_dwordx2 v[174:175], v[230:231], off offset:32
	global_load_dwordx2 v[176:177], v[230:231], off offset:256
	global_load_dwordx2 v[178:179], v[230:231], off offset:288
	v_add_co_u32_e32 v230, vcc, 0x10000, v152
	s_nop 1
	v_addc_co_u32_e32 v231, vcc, 0, v153, vcc
	global_load_dwordx2 v[180:181], v[230:231], off
	global_load_dwordx2 v[182:183], v[230:231], off offset:32
	global_load_dwordx2 v[184:185], v[230:231], off offset:256
	global_load_dwordx2 v[188:189], v[230:231], off offset:288
	v_add_co_u32_e32 v230, vcc, 0x18000, v152
	s_nop 1
	v_addc_co_u32_e32 v231, vcc, 0, v153, vcc
	global_load_dwordx2 v[190:191], v[230:231], off
	global_load_dwordx2 v[192:193], v[230:231], off offset:32
	global_load_dwordx2 v[194:195], v[230:231], off offset:256
	global_load_dwordx2 v[196:197], v[230:231], off offset:288
	v_add_co_u32_e32 v230, vcc, 0x40000, v152
	s_nop 1
	v_addc_co_u32_e32 v231, vcc, 0, v153, vcc
	global_load_dwordx2 v[198:199], v[230:231], off
	global_load_dwordx2 v[200:201], v[230:231], off offset:32
	global_load_dwordx2 v[202:203], v[230:231], off offset:256
	global_load_dwordx2 v[204:205], v[230:231], off offset:288
	v_add_co_u32_e32 v230, vcc, 0x48000, v152
	s_nop 1
	v_addc_co_u32_e32 v231, vcc, 0, v153, vcc
	global_load_dwordx2 v[206:207], v[230:231], off
	global_load_dwordx2 v[208:209], v[230:231], off offset:32
	global_load_dwordx2 v[210:211], v[230:231], off offset:256
	global_load_dwordx2 v[212:213], v[230:231], off offset:288
	v_add_co_u32_e32 v230, vcc, 0x50000, v152
	s_nop 1
	v_addc_co_u32_e32 v231, vcc, 0, v153, vcc
	global_load_dwordx2 v[214:215], v[230:231], off
	global_load_dwordx2 v[216:217], v[230:231], off offset:32
	global_load_dwordx2 v[218:219], v[230:231], off offset:256
	global_load_dwordx2 v[220:221], v[230:231], off offset:288
	v_add_co_u32_e32 v230, vcc, 0x58000, v152
	s_nop 1
	v_addc_co_u32_e32 v231, vcc, 0, v153, vcc
	global_load_dwordx2 v[222:223], v[230:231], off
	global_load_dwordx2 v[224:225], v[230:231], off offset:32
	global_load_dwordx2 v[226:227], v[230:231], off offset:256
	global_load_dwordx2 v[228:229], v[230:231], off offset:288
	s_waitcnt vmcnt(0)
	v_mbcnt_lo_u32_b32 v240, -1, 0
	v_mbcnt_hi_u32_b32 v240, -1, v240
	v_and_b32_e32 v240, 16, v240
	v_lshrrev_b32_e32 v241, 1, v240
	v_add_u32_e32 v240, v240, v241
	v_mov_b32_e32 v241, 0
	s_lshl_b32 s26, s10, 2
	s_ashr_i32 s27, s26, 31
	v_mov_b64_e32 v[154:155], v[164:165]
	v_lshlrev_b32_e32 v156, 16, v154
	v_and_b32_e32 v157, 0xffff0000, v154
	v_lshlrev_b32_e32 v154, 16, v155
	v_and_b32_e32 v155, 0xffff0000, v155
	v_pk_add_f32 v[126:127], v[126:127], v[154:155]
	v_pk_add_f32 v[124:125], v[124:125], v[156:157]
	s_nop 0
	v_cvt_pk_bf16_f32 v232, v124, v125
	v_cvt_pk_bf16_f32 v233, v126, v127
	v_mul_f32_e32 v125, v125, v125
	s_nop 0
	v_mul_f32_e32 v127, v127, v127
	v_fmac_f32_e32 v125, v124, v124
	v_fmac_f32_e32 v127, v126, v126
	v_add_f32_e32 v124, v125, v127
	v_mov_b64_e32 v[156:157], v[166:167]
	v_lshlrev_b32_e32 v154, 16, v156
	v_and_b32_e32 v155, 0xffff0000, v156
	v_lshlrev_b32_e32 v156, 16, v157
	v_and_b32_e32 v157, 0xffff0000, v157
	v_pk_add_f32 v[122:123], v[122:123], v[156:157]
	v_pk_add_f32 v[120:121], v[120:121], v[154:155]
	s_nop 0
	v_cvt_pk_bf16_f32 v234, v120, v121
	v_cvt_pk_bf16_f32 v235, v122, v123
	v_mul_f32_e32 v121, v121, v121
	s_nop 1
	v_permlane16_swap_b32_e32 v232, v234
	v_permlane16_swap_b32_e32 v233, v235
	v_lshl_add_u64 v[242:243], v[152:153], 0, v[240:241]
	global_store_dwordx4 v[242:243], v[232:235], off sc0 sc1
	v_mul_f32_e32 v123, v123, v123
	v_fmac_f32_e32 v121, v120, v120
	v_fmac_f32_e32 v123, v122, v122
	v_add_f32_e32 v120, v121, v123
	v_add_f32_e32 v120, v124, v120
	v_mov_b64_e32 v[156:157], v[168:169]
	v_lshlrev_b32_e32 v154, 16, v156
	v_and_b32_e32 v155, 0xffff0000, v156
	v_lshlrev_b32_e32 v156, 16, v157
	v_and_b32_e32 v157, 0xffff0000, v157
	v_pk_add_f32 v[118:119], v[118:119], v[156:157]
	v_pk_add_f32 v[154:155], v[116:117], v[154:155]
	v_and_b32_e32 v117, 64, v150
	v_cvt_pk_bf16_f32 v236, v154, v155
	v_cvt_pk_bf16_f32 v237, v118, v119
	v_mul_f32_e32 v121, v155, v155
	v_mul_f32_e32 v119, v119, v119
	v_fmac_f32_e32 v121, v154, v154
	v_fmac_f32_e32 v119, v118, v118
	v_add_f32_e32 v118, v121, v119
	v_add_f32_e32 v122, v120, v118
	v_xor_b32_e32 v116, 16, v150
	v_add_u32_e32 v117, 64, v117
	v_cmp_lt_i32_e32 vcc, v116, v117
	s_nop 0
	v_mov_b64_e32 v[158:159], v[170:171]
	v_lshlrev_b32_e32 v118, 16, v158
	v_and_b32_e32 v119, 0xffff0000, v158
	v_lshlrev_b32_e32 v120, 16, v159
	v_and_b32_e32 v121, 0xffff0000, v159
	v_pk_add_f32 v[120:121], v[114:115], v[120:121]
	v_pk_add_f32 v[118:119], v[112:113], v[118:119]
	v_mul_f32_e32 v113, v121, v121
	v_mul_f32_e32 v112, v119, v119
	v_fmac_f32_e32 v112, v118, v118
	v_fmac_f32_e32 v113, v120, v120
	v_cndmask_b32_e32 v116, v150, v116, vcc
	v_add_f32_e32 v112, v112, v113
	v_lshlrev_b32_e32 v116, 2, v116
	v_add_f32_e32 v112, v122, v112
	ds_bpermute_b32 v113, v116, v112
	v_xor_b32_e32 v114, 32, v150
	v_cmp_lt_i32_e32 vcc, v114, v117
	v_cvt_pk_bf16_f32 v238, v118, v119
	v_cvt_pk_bf16_f32 v239, v120, v121
	s_waitcnt lgkmcnt(0)
	v_add_f32_e32 v112, v112, v113
	s_nop 1
	v_permlane16_swap_b32_e32 v236, v238
	v_permlane16_swap_b32_e32 v237, v239
	v_lshl_add_u64 v[242:243], v[152:153], 0, v[240:241]
	global_store_dwordx4 v[242:243], v[236:239], off offset:256 sc0 sc1
	v_cndmask_b32_e32 v114, v150, v114, vcc
	v_lshlrev_b32_e32 v114, 2, v114
	ds_bpermute_b32 v113, v114, v112
	s_and_saveexec_b64 s[28:29], s[4:5]
	s_cbranch_execz .LBB0_934
	s_waitcnt lgkmcnt(0)
	v_add_f32_e32 v115, v112, v113
	v_lshlrev_b64 v[112:113], 6, v[144:145]
	v_lshl_add_u64 v[112:113], s[60:61], 0, v[112:113]
	v_lshl_add_u64 v[112:113], s[26:27], 2, v[112:113]
	s_lshl_b32 s10, s44, 2
	v_lshl_add_u64 v[112:113], v[112:113], 0, s[10:11]
	global_store_dword v[112:113], v115, off
.LBB0_934:
	s_or_b64 exec, exec, s[28:29]
	v_or_b32_e32 v112, 16, v144
	s_waitcnt lgkmcnt(0)
	v_ashrrev_i32_e32 v113, 31, v112
	v_lshlrev_b64 v[118:119], 11, v[112:113]
	v_lshl_add_u64 v[118:119], s[62:63], 0, v[118:119]
	v_lshl_add_u64 v[118:119], v[142:143], 1, v[118:119]
	v_mov_b64_e32 v[120:121], v[172:173]
	v_lshlrev_b32_e32 v122, 16, v120
	v_and_b32_e32 v123, 0xffff0000, v120
	v_lshlrev_b32_e32 v120, 16, v121
	v_and_b32_e32 v121, 0xffff0000, v121
	v_pk_add_f32 v[110:111], v[110:111], v[120:121]
	v_pk_add_f32 v[108:109], v[108:109], v[122:123]
	s_nop 0
	v_cvt_pk_bf16_f32 v232, v108, v109
	v_cvt_pk_bf16_f32 v233, v110, v111
	v_mul_f32_e32 v109, v109, v109
	s_nop 0
	v_mul_f32_e32 v111, v111, v111
	v_fmac_f32_e32 v109, v108, v108
	v_fmac_f32_e32 v111, v110, v110
	v_add_f32_e32 v108, v109, v111
	v_mov_b64_e32 v[122:123], v[174:175]
	v_lshlrev_b32_e32 v120, 16, v122
	v_and_b32_e32 v121, 0xffff0000, v122
	v_lshlrev_b32_e32 v122, 16, v123
	v_and_b32_e32 v123, 0xffff0000, v123
	v_pk_add_f32 v[106:107], v[106:107], v[122:123]
	v_pk_add_f32 v[104:105], v[104:105], v[120:121]
	s_nop 0
	v_cvt_pk_bf16_f32 v234, v104, v105
	v_cvt_pk_bf16_f32 v235, v106, v107
	v_mul_f32_e32 v105, v105, v105
	s_nop 1
	v_permlane16_swap_b32_e32 v232, v234
	v_permlane16_swap_b32_e32 v233, v235
	v_lshl_add_u64 v[242:243], v[118:119], 0, v[240:241]
	global_store_dwordx4 v[242:243], v[232:235], off sc0 sc1
	v_mul_f32_e32 v107, v107, v107
	v_fmac_f32_e32 v105, v104, v104
	v_fmac_f32_e32 v107, v106, v106
	v_add_f32_e32 v104, v105, v107
	v_add_f32_e32 v104, v108, v104
	v_mov_b64_e32 v[122:123], v[176:177]
	v_lshlrev_b32_e32 v120, 16, v122
	v_and_b32_e32 v121, 0xffff0000, v122
	v_lshlrev_b32_e32 v122, 16, v123
	v_and_b32_e32 v123, 0xffff0000, v123
	v_pk_add_f32 v[102:103], v[102:103], v[122:123]
	v_pk_add_f32 v[100:101], v[100:101], v[120:121]
	s_nop 0
	v_cvt_pk_bf16_f32 v236, v100, v101
	v_cvt_pk_bf16_f32 v237, v102, v103
	v_mul_f32_e32 v101, v101, v101
	v_mul_f32_e32 v103, v103, v103
	v_fmac_f32_e32 v101, v100, v100
	v_fmac_f32_e32 v103, v102, v102
	v_add_f32_e32 v100, v101, v103
	v_add_f32_e32 v104, v104, v100
	s_nop 0
	v_mov_b64_e32 v[122:123], v[178:179]
	v_lshlrev_b32_e32 v100, 16, v122
	v_and_b32_e32 v101, 0xffff0000, v122
	v_lshlrev_b32_e32 v102, 16, v123
	v_and_b32_e32 v103, 0xffff0000, v123
	v_pk_add_f32 v[98:99], v[98:99], v[102:103]
	v_pk_add_f32 v[100:101], v[96:97], v[100:101]
	v_mul_f32_e32 v97, v99, v99
	v_mul_f32_e32 v96, v101, v101
	v_fmac_f32_e32 v96, v100, v100
	v_fmac_f32_e32 v97, v98, v98
	v_add_f32_e32 v96, v96, v97
	v_add_f32_e32 v96, v104, v96
	ds_bpermute_b32 v97, v116, v96
	v_cvt_pk_bf16_f32 v238, v100, v101
	v_cvt_pk_bf16_f32 v239, v98, v99
	s_nop 1
	v_permlane16_swap_b32_e32 v236, v238
	v_permlane16_swap_b32_e32 v237, v239
	v_lshl_add_u64 v[242:243], v[118:119], 0, v[240:241]
	global_store_dwordx4 v[242:243], v[236:239], off offset:256 sc0 sc1
	s_waitcnt lgkmcnt(0)
	v_add_f32_e32 v96, v96, v97
	ds_bpermute_b32 v97, v114, v96
	s_and_saveexec_b64 s[28:29], s[4:5]
	s_cbranch_execz .LBB0_936
	s_waitcnt lgkmcnt(0)
	v_add_f32_e32 v98, v96, v97
	v_lshlrev_b64 v[96:97], 6, v[112:113]
	v_lshl_add_u64 v[96:97], s[60:61], 0, v[96:97]
	v_lshl_add_u64 v[96:97], s[26:27], 2, v[96:97]
	s_lshl_b32 s10, s44, 2
	v_lshl_add_u64 v[96:97], v[96:97], 0, s[10:11]
	global_store_dword v[96:97], v98, off
.LBB0_936:
	s_or_b64 exec, exec, s[28:29]
	v_or_b32_e32 v96, 32, v144
	s_waitcnt lgkmcnt(0)
	v_ashrrev_i32_e32 v97, 31, v96
	v_lshlrev_b64 v[98:99], 11, v[96:97]
	v_lshl_add_u64 v[98:99], s[62:63], 0, v[98:99]
	v_lshl_add_u64 v[98:99], v[142:143], 1, v[98:99]
	v_mov_b64_e32 v[100:101], v[180:181]
	v_lshlrev_b32_e32 v102, 16, v100
	v_and_b32_e32 v103, 0xffff0000, v100
	v_lshlrev_b32_e32 v100, 16, v101
	v_and_b32_e32 v101, 0xffff0000, v101
	v_pk_add_f32 v[94:95], v[94:95], v[100:101]
	v_pk_add_f32 v[92:93], v[92:93], v[102:103]
	s_nop 0
	v_cvt_pk_bf16_f32 v232, v92, v93
	v_cvt_pk_bf16_f32 v233, v94, v95
	v_mul_f32_e32 v93, v93, v93
	s_nop 0
	v_mul_f32_e32 v95, v95, v95
	v_fmac_f32_e32 v93, v92, v92
	v_fmac_f32_e32 v95, v94, v94
	v_add_f32_e32 v92, v93, v95
	v_mov_b64_e32 v[102:103], v[182:183]
	v_lshlrev_b32_e32 v100, 16, v102
	v_and_b32_e32 v101, 0xffff0000, v102
	v_lshlrev_b32_e32 v102, 16, v103
	v_and_b32_e32 v103, 0xffff0000, v103
	v_pk_add_f32 v[90:91], v[90:91], v[102:103]
	v_pk_add_f32 v[88:89], v[88:89], v[100:101]
	s_nop 0
	v_cvt_pk_bf16_f32 v234, v88, v89
	v_cvt_pk_bf16_f32 v235, v90, v91
	v_mul_f32_e32 v89, v89, v89
	s_nop 1
	v_permlane16_swap_b32_e32 v232, v234
	v_permlane16_swap_b32_e32 v233, v235
	v_lshl_add_u64 v[242:243], v[98:99], 0, v[240:241]
	global_store_dwordx4 v[242:243], v[232:235], off sc0 sc1
	v_mul_f32_e32 v91, v91, v91
	v_fmac_f32_e32 v89, v88, v88
	v_fmac_f32_e32 v91, v90, v90
	v_add_f32_e32 v88, v89, v91
	v_add_f32_e32 v88, v92, v88
	v_mov_b64_e32 v[102:103], v[184:185]
	v_lshlrev_b32_e32 v100, 16, v102
	v_and_b32_e32 v101, 0xffff0000, v102
	v_lshlrev_b32_e32 v102, 16, v103
	v_and_b32_e32 v103, 0xffff0000, v103
	v_pk_add_f32 v[86:87], v[86:87], v[102:103]
	v_pk_add_f32 v[84:85], v[84:85], v[100:101]
	s_nop 0
	v_cvt_pk_bf16_f32 v236, v84, v85
	v_cvt_pk_bf16_f32 v237, v86, v87
	v_mul_f32_e32 v85, v85, v85
	v_mul_f32_e32 v87, v87, v87
	v_fmac_f32_e32 v85, v84, v84
	v_fmac_f32_e32 v87, v86, v86
	v_add_f32_e32 v84, v85, v87
	v_add_f32_e32 v88, v88, v84
	s_nop 0
	v_mov_b64_e32 v[102:103], v[188:189]
	v_lshlrev_b32_e32 v84, 16, v102
	v_and_b32_e32 v85, 0xffff0000, v102
	v_lshlrev_b32_e32 v86, 16, v103
	v_and_b32_e32 v87, 0xffff0000, v103
	v_pk_add_f32 v[82:83], v[82:83], v[86:87]
	v_pk_add_f32 v[84:85], v[80:81], v[84:85]
	v_mul_f32_e32 v81, v83, v83
	v_mul_f32_e32 v80, v85, v85
	v_fmac_f32_e32 v80, v84, v84
	v_fmac_f32_e32 v81, v82, v82
	v_add_f32_e32 v80, v80, v81
	v_add_f32_e32 v80, v88, v80
	ds_bpermute_b32 v81, v116, v80
	v_cvt_pk_bf16_f32 v238, v84, v85
	v_cvt_pk_bf16_f32 v239, v82, v83
	s_nop 1
	v_permlane16_swap_b32_e32 v236, v238
	v_permlane16_swap_b32_e32 v237, v239
	v_lshl_add_u64 v[242:243], v[98:99], 0, v[240:241]
	global_store_dwordx4 v[242:243], v[236:239], off offset:256 sc0 sc1
	s_waitcnt lgkmcnt(0)
	v_add_f32_e32 v80, v80, v81
	ds_bpermute_b32 v81, v114, v80
	s_and_saveexec_b64 s[28:29], s[4:5]
	s_cbranch_execz .LBB0_938
	s_waitcnt lgkmcnt(0)
	v_add_f32_e32 v82, v80, v81
	v_lshlrev_b64 v[80:81], 6, v[96:97]
	v_lshl_add_u64 v[80:81], s[60:61], 0, v[80:81]
	v_lshl_add_u64 v[80:81], s[26:27], 2, v[80:81]
	s_lshl_b32 s10, s44, 2
	v_lshl_add_u64 v[80:81], v[80:81], 0, s[10:11]
	global_store_dword v[80:81], v82, off
.LBB0_938:
	s_or_b64 exec, exec, s[28:29]
	v_or_b32_e32 v80, 48, v144
	s_waitcnt lgkmcnt(0)
	v_ashrrev_i32_e32 v81, 31, v80
	v_lshlrev_b64 v[82:83], 11, v[80:81]
	v_lshl_add_u64 v[82:83], s[62:63], 0, v[82:83]
	v_lshl_add_u64 v[82:83], v[142:143], 1, v[82:83]
	v_mov_b64_e32 v[84:85], v[190:191]
	v_lshlrev_b32_e32 v86, 16, v84
	v_and_b32_e32 v87, 0xffff0000, v84
	v_lshlrev_b32_e32 v84, 16, v85
	v_and_b32_e32 v85, 0xffff0000, v85
	v_pk_add_f32 v[78:79], v[78:79], v[84:85]
	v_pk_add_f32 v[76:77], v[76:77], v[86:87]
	s_nop 0
	v_cvt_pk_bf16_f32 v232, v76, v77
	v_cvt_pk_bf16_f32 v233, v78, v79
	v_mul_f32_e32 v77, v77, v77
	s_nop 0
	v_mul_f32_e32 v79, v79, v79
	v_fmac_f32_e32 v77, v76, v76
	v_fmac_f32_e32 v79, v78, v78
	v_add_f32_e32 v76, v77, v79
	v_mov_b64_e32 v[86:87], v[192:193]
	v_lshlrev_b32_e32 v84, 16, v86
	v_and_b32_e32 v85, 0xffff0000, v86
	v_lshlrev_b32_e32 v86, 16, v87
	v_and_b32_e32 v87, 0xffff0000, v87
	v_pk_add_f32 v[74:75], v[74:75], v[86:87]
	v_pk_add_f32 v[72:73], v[72:73], v[84:85]
	s_nop 0
	v_cvt_pk_bf16_f32 v234, v72, v73
	v_cvt_pk_bf16_f32 v235, v74, v75
	v_mul_f32_e32 v73, v73, v73
	s_nop 1
	v_permlane16_swap_b32_e32 v232, v234
	v_permlane16_swap_b32_e32 v233, v235
	v_lshl_add_u64 v[242:243], v[82:83], 0, v[240:241]
	global_store_dwordx4 v[242:243], v[232:235], off sc0 sc1
	v_mul_f32_e32 v75, v75, v75
	v_fmac_f32_e32 v73, v72, v72
	v_fmac_f32_e32 v75, v74, v74
	v_add_f32_e32 v72, v73, v75
	v_add_f32_e32 v72, v76, v72
	v_mov_b64_e32 v[86:87], v[194:195]
	v_lshlrev_b32_e32 v84, 16, v86
	v_and_b32_e32 v85, 0xffff0000, v86
	v_lshlrev_b32_e32 v86, 16, v87
	v_and_b32_e32 v87, 0xffff0000, v87
	v_pk_add_f32 v[70:71], v[70:71], v[86:87]
	v_pk_add_f32 v[68:69], v[68:69], v[84:85]
	s_nop 0
	v_cvt_pk_bf16_f32 v236, v68, v69
	v_cvt_pk_bf16_f32 v237, v70, v71
	v_mul_f32_e32 v69, v69, v69
	v_mul_f32_e32 v71, v71, v71
	v_fmac_f32_e32 v69, v68, v68
	v_fmac_f32_e32 v71, v70, v70
	v_add_f32_e32 v68, v69, v71
	v_add_f32_e32 v72, v72, v68
	s_nop 0
	v_mov_b64_e32 v[86:87], v[196:197]
	v_lshlrev_b32_e32 v68, 16, v86
	v_and_b32_e32 v69, 0xffff0000, v86
	v_lshlrev_b32_e32 v70, 16, v87
	v_and_b32_e32 v71, 0xffff0000, v87
	v_pk_add_f32 v[66:67], v[66:67], v[70:71]
	v_pk_add_f32 v[68:69], v[64:65], v[68:69]
	v_mul_f32_e32 v65, v67, v67
	v_mul_f32_e32 v64, v69, v69
	v_fmac_f32_e32 v64, v68, v68
	v_fmac_f32_e32 v65, v66, v66
	v_add_f32_e32 v64, v64, v65
	v_add_f32_e32 v64, v72, v64
	ds_bpermute_b32 v65, v116, v64
	v_cvt_pk_bf16_f32 v238, v68, v69
	v_cvt_pk_bf16_f32 v239, v66, v67
	s_nop 1
	v_permlane16_swap_b32_e32 v236, v238
	v_permlane16_swap_b32_e32 v237, v239
	v_lshl_add_u64 v[242:243], v[82:83], 0, v[240:241]
	global_store_dwordx4 v[242:243], v[236:239], off offset:256 sc0 sc1
	s_waitcnt lgkmcnt(0)
	v_add_f32_e32 v64, v64, v65
	ds_bpermute_b32 v65, v114, v64
	s_and_saveexec_b64 s[28:29], s[4:5]
	s_cbranch_execz .LBB0_940
	s_waitcnt lgkmcnt(0)
	v_add_f32_e32 v66, v64, v65
	v_lshlrev_b64 v[64:65], 6, v[80:81]
	v_lshl_add_u64 v[64:65], s[60:61], 0, v[64:65]
	v_lshl_add_u64 v[64:65], s[26:27], 2, v[64:65]
	s_lshl_b32 s10, s44, 2
	v_lshl_add_u64 v[64:65], v[64:65], 0, s[10:11]
	global_store_dword v[64:65], v66, off
.LBB0_940:
	s_or_b64 exec, exec, s[28:29]
	v_add_u32_e32 v64, 0x80, v144
	s_waitcnt lgkmcnt(0)
	v_ashrrev_i32_e32 v65, 31, v64
	v_lshlrev_b64 v[66:67], 11, v[64:65]
	v_lshl_add_u64 v[66:67], s[62:63], 0, v[66:67]
	v_lshl_add_u64 v[66:67], v[142:143], 1, v[66:67]
	v_mov_b64_e32 v[68:69], v[198:199]
	v_lshlrev_b32_e32 v70, 16, v68
	v_and_b32_e32 v71, 0xffff0000, v68
	v_lshlrev_b32_e32 v68, 16, v69
	v_and_b32_e32 v69, 0xffff0000, v69
	v_pk_add_f32 v[62:63], v[62:63], v[68:69]
	v_pk_add_f32 v[60:61], v[60:61], v[70:71]
	s_nop 0
	v_cvt_pk_bf16_f32 v232, v60, v61
	v_cvt_pk_bf16_f32 v233, v62, v63
	v_mul_f32_e32 v61, v61, v61
	s_nop 0
	v_mul_f32_e32 v63, v63, v63
	v_fmac_f32_e32 v61, v60, v60
	v_fmac_f32_e32 v63, v62, v62
	v_add_f32_e32 v60, v61, v63
	v_mov_b64_e32 v[70:71], v[200:201]
	v_lshlrev_b32_e32 v68, 16, v70
	v_and_b32_e32 v69, 0xffff0000, v70
	v_lshlrev_b32_e32 v70, 16, v71
	v_and_b32_e32 v71, 0xffff0000, v71
	v_pk_add_f32 v[58:59], v[58:59], v[70:71]
	v_pk_add_f32 v[56:57], v[56:57], v[68:69]
	s_nop 0
	v_cvt_pk_bf16_f32 v234, v56, v57
	v_cvt_pk_bf16_f32 v235, v58, v59
	v_mul_f32_e32 v57, v57, v57
	s_nop 1
	v_permlane16_swap_b32_e32 v232, v234
	v_permlane16_swap_b32_e32 v233, v235
	v_lshl_add_u64 v[242:243], v[66:67], 0, v[240:241]
	global_store_dwordx4 v[242:243], v[232:235], off sc0 sc1
	v_mul_f32_e32 v59, v59, v59
	v_fmac_f32_e32 v57, v56, v56
	v_fmac_f32_e32 v59, v58, v58
	v_add_f32_e32 v56, v57, v59
	v_add_f32_e32 v56, v60, v56
	v_mov_b64_e32 v[70:71], v[202:203]
	v_lshlrev_b32_e32 v68, 16, v70
	v_and_b32_e32 v69, 0xffff0000, v70
	v_lshlrev_b32_e32 v70, 16, v71
	v_and_b32_e32 v71, 0xffff0000, v71
	v_pk_add_f32 v[54:55], v[54:55], v[70:71]
	v_pk_add_f32 v[52:53], v[52:53], v[68:69]
	s_nop 0
	v_cvt_pk_bf16_f32 v236, v52, v53
	v_cvt_pk_bf16_f32 v237, v54, v55
	v_mul_f32_e32 v53, v53, v53
	v_mul_f32_e32 v55, v55, v55
	v_fmac_f32_e32 v53, v52, v52
	v_fmac_f32_e32 v55, v54, v54
	v_add_f32_e32 v52, v53, v55
	v_add_f32_e32 v56, v56, v52
	s_nop 0
	v_mov_b64_e32 v[70:71], v[204:205]
	v_lshlrev_b32_e32 v52, 16, v70
	v_and_b32_e32 v53, 0xffff0000, v70
	v_lshlrev_b32_e32 v54, 16, v71
	v_and_b32_e32 v55, 0xffff0000, v71
	v_pk_add_f32 v[50:51], v[50:51], v[54:55]
	v_pk_add_f32 v[52:53], v[48:49], v[52:53]
	v_mul_f32_e32 v49, v51, v51
	v_mul_f32_e32 v48, v53, v53
	v_fmac_f32_e32 v48, v52, v52
	v_fmac_f32_e32 v49, v50, v50
	v_add_f32_e32 v48, v48, v49
	v_add_f32_e32 v48, v56, v48
	ds_bpermute_b32 v49, v116, v48
	v_cvt_pk_bf16_f32 v238, v52, v53
	v_cvt_pk_bf16_f32 v239, v50, v51
	s_nop 1
	v_permlane16_swap_b32_e32 v236, v238
	v_permlane16_swap_b32_e32 v237, v239
	v_lshl_add_u64 v[242:243], v[66:67], 0, v[240:241]
	global_store_dwordx4 v[242:243], v[236:239], off offset:256 sc0 sc1
	s_waitcnt lgkmcnt(0)
	v_add_f32_e32 v48, v48, v49
	ds_bpermute_b32 v49, v114, v48
	s_and_saveexec_b64 s[28:29], s[4:5]
	s_cbranch_execz .LBB0_942
	s_waitcnt lgkmcnt(0)
	v_add_f32_e32 v50, v48, v49
	v_lshlrev_b64 v[48:49], 6, v[64:65]
	v_lshl_add_u64 v[48:49], s[60:61], 0, v[48:49]
	v_lshl_add_u64 v[48:49], s[26:27], 2, v[48:49]
	s_lshl_b32 s10, s44, 2
	v_lshl_add_u64 v[48:49], v[48:49], 0, s[10:11]
	global_store_dword v[48:49], v50, off
.LBB0_942:
	s_or_b64 exec, exec, s[28:29]
	v_add_u32_e32 v48, 0x90, v144
	s_waitcnt lgkmcnt(0)
	v_ashrrev_i32_e32 v49, 31, v48
	v_lshlrev_b64 v[50:51], 11, v[48:49]
	v_lshl_add_u64 v[50:51], s[62:63], 0, v[50:51]
	v_lshl_add_u64 v[50:51], v[142:143], 1, v[50:51]
	v_mov_b64_e32 v[52:53], v[206:207]
	v_lshlrev_b32_e32 v54, 16, v52
	v_and_b32_e32 v55, 0xffff0000, v52
	v_lshlrev_b32_e32 v52, 16, v53
	v_and_b32_e32 v53, 0xffff0000, v53
	v_pk_add_f32 v[46:47], v[46:47], v[52:53]
	v_pk_add_f32 v[44:45], v[44:45], v[54:55]
	s_nop 0
	v_cvt_pk_bf16_f32 v232, v44, v45
	v_cvt_pk_bf16_f32 v233, v46, v47
	v_mul_f32_e32 v45, v45, v45
	s_nop 0
	v_mul_f32_e32 v47, v47, v47
	v_fmac_f32_e32 v45, v44, v44
	v_fmac_f32_e32 v47, v46, v46
	v_add_f32_e32 v44, v45, v47
	v_mov_b64_e32 v[54:55], v[208:209]
	v_lshlrev_b32_e32 v52, 16, v54
	v_and_b32_e32 v53, 0xffff0000, v54
	v_lshlrev_b32_e32 v54, 16, v55
	v_and_b32_e32 v55, 0xffff0000, v55
	v_pk_add_f32 v[42:43], v[42:43], v[54:55]
	v_pk_add_f32 v[40:41], v[40:41], v[52:53]
	s_nop 0
	v_cvt_pk_bf16_f32 v234, v40, v41
	v_cvt_pk_bf16_f32 v235, v42, v43
	v_mul_f32_e32 v41, v41, v41
	s_nop 1
	v_permlane16_swap_b32_e32 v232, v234
	v_permlane16_swap_b32_e32 v233, v235
	v_lshl_add_u64 v[242:243], v[50:51], 0, v[240:241]
	global_store_dwordx4 v[242:243], v[232:235], off sc0 sc1
	v_mul_f32_e32 v43, v43, v43
	v_fmac_f32_e32 v41, v40, v40
	v_fmac_f32_e32 v43, v42, v42
	v_add_f32_e32 v40, v41, v43
	v_add_f32_e32 v40, v44, v40
	v_mov_b64_e32 v[54:55], v[210:211]
	v_lshlrev_b32_e32 v52, 16, v54
	v_and_b32_e32 v53, 0xffff0000, v54
	v_lshlrev_b32_e32 v54, 16, v55
	v_and_b32_e32 v55, 0xffff0000, v55
	v_pk_add_f32 v[38:39], v[38:39], v[54:55]
	v_pk_add_f32 v[36:37], v[36:37], v[52:53]
	s_nop 0
	v_cvt_pk_bf16_f32 v236, v36, v37
	v_cvt_pk_bf16_f32 v237, v38, v39
	v_mul_f32_e32 v37, v37, v37
	v_mul_f32_e32 v39, v39, v39
	v_fmac_f32_e32 v37, v36, v36
	v_fmac_f32_e32 v39, v38, v38
	v_add_f32_e32 v36, v37, v39
	v_add_f32_e32 v40, v40, v36
	s_nop 0
	v_mov_b64_e32 v[54:55], v[212:213]
	v_lshlrev_b32_e32 v36, 16, v54
	v_and_b32_e32 v37, 0xffff0000, v54
	v_lshlrev_b32_e32 v38, 16, v55
	v_and_b32_e32 v39, 0xffff0000, v55
	v_pk_add_f32 v[34:35], v[34:35], v[38:39]
	v_pk_add_f32 v[36:37], v[32:33], v[36:37]
	v_mul_f32_e32 v33, v35, v35
	v_mul_f32_e32 v32, v37, v37
	v_fmac_f32_e32 v32, v36, v36
	v_fmac_f32_e32 v33, v34, v34
	v_add_f32_e32 v32, v32, v33
	v_add_f32_e32 v32, v40, v32
	ds_bpermute_b32 v33, v116, v32
	v_cvt_pk_bf16_f32 v238, v36, v37
	v_cvt_pk_bf16_f32 v239, v34, v35
	s_nop 1
	v_permlane16_swap_b32_e32 v236, v238
	v_permlane16_swap_b32_e32 v237, v239
	v_lshl_add_u64 v[242:243], v[50:51], 0, v[240:241]
	global_store_dwordx4 v[242:243], v[236:239], off offset:256 sc0 sc1
	s_waitcnt lgkmcnt(0)
	v_add_f32_e32 v32, v32, v33
	ds_bpermute_b32 v33, v114, v32
	s_and_saveexec_b64 s[28:29], s[4:5]
	s_cbranch_execz .LBB0_944
	s_waitcnt lgkmcnt(0)
	v_add_f32_e32 v34, v32, v33
	v_lshlrev_b64 v[32:33], 6, v[48:49]
	v_lshl_add_u64 v[32:33], s[60:61], 0, v[32:33]
	v_lshl_add_u64 v[32:33], s[26:27], 2, v[32:33]
	s_lshl_b32 s10, s44, 2
	v_lshl_add_u64 v[32:33], v[32:33], 0, s[10:11]
	global_store_dword v[32:33], v34, off
.LBB0_944:
	s_or_b64 exec, exec, s[28:29]
	v_add_u32_e32 v32, 0xa0, v144
	s_waitcnt lgkmcnt(0)
	v_ashrrev_i32_e32 v33, 31, v32
	v_lshlrev_b64 v[34:35], 11, v[32:33]
	v_lshl_add_u64 v[34:35], s[62:63], 0, v[34:35]
	v_lshl_add_u64 v[34:35], v[142:143], 1, v[34:35]
	v_mov_b64_e32 v[36:37], v[214:215]
	v_lshlrev_b32_e32 v38, 16, v36
	v_and_b32_e32 v39, 0xffff0000, v36
	v_lshlrev_b32_e32 v36, 16, v37
	v_and_b32_e32 v37, 0xffff0000, v37
	v_pk_add_f32 v[30:31], v[30:31], v[36:37]
	v_pk_add_f32 v[28:29], v[28:29], v[38:39]
	s_nop 0
	v_cvt_pk_bf16_f32 v232, v28, v29
	v_cvt_pk_bf16_f32 v233, v30, v31
	v_mul_f32_e32 v29, v29, v29
	s_nop 0
	v_mul_f32_e32 v31, v31, v31
	v_fmac_f32_e32 v29, v28, v28
	v_fmac_f32_e32 v31, v30, v30
	v_add_f32_e32 v28, v29, v31
	v_mov_b64_e32 v[38:39], v[216:217]
	v_lshlrev_b32_e32 v36, 16, v38
	v_and_b32_e32 v37, 0xffff0000, v38
	v_lshlrev_b32_e32 v38, 16, v39
	v_and_b32_e32 v39, 0xffff0000, v39
	v_pk_add_f32 v[26:27], v[26:27], v[38:39]
	v_pk_add_f32 v[24:25], v[24:25], v[36:37]
	s_nop 0
	v_cvt_pk_bf16_f32 v234, v24, v25
	v_cvt_pk_bf16_f32 v235, v26, v27
	v_mul_f32_e32 v25, v25, v25
	s_nop 1
	v_permlane16_swap_b32_e32 v232, v234
	v_permlane16_swap_b32_e32 v233, v235
	v_lshl_add_u64 v[242:243], v[34:35], 0, v[240:241]
	global_store_dwordx4 v[242:243], v[232:235], off sc0 sc1
	v_mul_f32_e32 v27, v27, v27
	v_fmac_f32_e32 v25, v24, v24
	v_fmac_f32_e32 v27, v26, v26
	v_add_f32_e32 v24, v25, v27
	v_add_f32_e32 v24, v28, v24
	v_mov_b64_e32 v[38:39], v[218:219]
	v_lshlrev_b32_e32 v36, 16, v38
	v_and_b32_e32 v37, 0xffff0000, v38
	v_lshlrev_b32_e32 v38, 16, v39
	v_and_b32_e32 v39, 0xffff0000, v39
	v_pk_add_f32 v[22:23], v[22:23], v[38:39]
	v_pk_add_f32 v[20:21], v[20:21], v[36:37]
	s_nop 0
	v_cvt_pk_bf16_f32 v236, v20, v21
	v_cvt_pk_bf16_f32 v237, v22, v23
	v_mul_f32_e32 v21, v21, v21
	v_mul_f32_e32 v23, v23, v23
	v_fmac_f32_e32 v21, v20, v20
	v_fmac_f32_e32 v23, v22, v22
	v_add_f32_e32 v20, v21, v23
	v_add_f32_e32 v24, v24, v20
	s_nop 0
	v_mov_b64_e32 v[38:39], v[220:221]
	v_lshlrev_b32_e32 v20, 16, v38
	v_and_b32_e32 v21, 0xffff0000, v38
	v_lshlrev_b32_e32 v22, 16, v39
	v_and_b32_e32 v23, 0xffff0000, v39
	v_pk_add_f32 v[18:19], v[18:19], v[22:23]
	v_pk_add_f32 v[20:21], v[16:17], v[20:21]
	v_mul_f32_e32 v17, v19, v19
	v_mul_f32_e32 v16, v21, v21
	v_fmac_f32_e32 v16, v20, v20
	v_fmac_f32_e32 v17, v18, v18
	v_add_f32_e32 v16, v16, v17
	v_add_f32_e32 v16, v24, v16
	ds_bpermute_b32 v17, v116, v16
	v_cvt_pk_bf16_f32 v238, v20, v21
	v_cvt_pk_bf16_f32 v239, v18, v19
	s_nop 1
	v_permlane16_swap_b32_e32 v236, v238
	v_permlane16_swap_b32_e32 v237, v239
	v_lshl_add_u64 v[242:243], v[34:35], 0, v[240:241]
	global_store_dwordx4 v[242:243], v[236:239], off offset:256 sc0 sc1
	s_waitcnt lgkmcnt(0)
	v_add_f32_e32 v16, v16, v17
	ds_bpermute_b32 v17, v114, v16
	s_and_saveexec_b64 s[28:29], s[4:5]
	s_cbranch_execz .LBB0_946
	s_waitcnt lgkmcnt(0)
	v_add_f32_e32 v18, v16, v17
	v_lshlrev_b64 v[16:17], 6, v[32:33]
	v_lshl_add_u64 v[16:17], s[60:61], 0, v[16:17]
	v_lshl_add_u64 v[16:17], s[26:27], 2, v[16:17]
	s_lshl_b32 s10, s44, 2
	v_lshl_add_u64 v[16:17], v[16:17], 0, s[10:11]
	global_store_dword v[16:17], v18, off
.LBB0_946:
	s_or_b64 exec, exec, s[28:29]
	v_add_u32_e32 v16, 0xb0, v144
	s_waitcnt lgkmcnt(0)
	v_ashrrev_i32_e32 v17, 31, v16
	v_lshlrev_b64 v[18:19], 11, v[16:17]
	v_lshl_add_u64 v[18:19], s[62:63], 0, v[18:19]
	v_lshl_add_u64 v[18:19], v[142:143], 1, v[18:19]
	v_mov_b64_e32 v[20:21], v[222:223]
	v_lshlrev_b32_e32 v22, 16, v20
	v_and_b32_e32 v23, 0xffff0000, v20
	v_lshlrev_b32_e32 v20, 16, v21
	v_and_b32_e32 v21, 0xffff0000, v21
	v_pk_add_f32 v[14:15], v[14:15], v[20:21]
	v_pk_add_f32 v[12:13], v[12:13], v[22:23]
	s_nop 0
	v_cvt_pk_bf16_f32 v232, v12, v13
	v_cvt_pk_bf16_f32 v233, v14, v15
	v_mul_f32_e32 v13, v13, v13
	s_nop 0
	v_mul_f32_e32 v15, v15, v15
	v_fmac_f32_e32 v13, v12, v12
	v_fmac_f32_e32 v15, v14, v14
	v_add_f32_e32 v12, v13, v15
	v_mov_b64_e32 v[22:23], v[224:225]
	v_lshlrev_b32_e32 v20, 16, v22
	v_and_b32_e32 v21, 0xffff0000, v22
	v_lshlrev_b32_e32 v22, 16, v23
	v_and_b32_e32 v23, 0xffff0000, v23
	v_pk_add_f32 v[10:11], v[10:11], v[22:23]
	v_pk_add_f32 v[8:9], v[8:9], v[20:21]
	s_nop 0
	v_cvt_pk_bf16_f32 v234, v8, v9
	v_cvt_pk_bf16_f32 v235, v10, v11
	v_mul_f32_e32 v9, v9, v9
	s_nop 1
	v_permlane16_swap_b32_e32 v232, v234
	v_permlane16_swap_b32_e32 v233, v235
	v_lshl_add_u64 v[242:243], v[18:19], 0, v[240:241]
	global_store_dwordx4 v[242:243], v[232:235], off sc0 sc1
	v_mul_f32_e32 v11, v11, v11
	v_fmac_f32_e32 v9, v8, v8
	v_fmac_f32_e32 v11, v10, v10
	v_add_f32_e32 v8, v9, v11
	v_add_f32_e32 v8, v12, v8
	v_mov_b64_e32 v[22:23], v[226:227]
	v_lshlrev_b32_e32 v20, 16, v22
	v_and_b32_e32 v21, 0xffff0000, v22
	v_lshlrev_b32_e32 v22, 16, v23
	v_and_b32_e32 v23, 0xffff0000, v23
	v_pk_add_f32 v[6:7], v[6:7], v[22:23]
	v_pk_add_f32 v[4:5], v[4:5], v[20:21]
	s_nop 0
	v_cvt_pk_bf16_f32 v236, v4, v5
	v_cvt_pk_bf16_f32 v237, v6, v7
	v_mul_f32_e32 v5, v5, v5
	v_mul_f32_e32 v7, v7, v7
	v_fmac_f32_e32 v5, v4, v4
	v_fmac_f32_e32 v7, v6, v6
	v_add_f32_e32 v4, v5, v7
	v_add_f32_e32 v8, v8, v4
	s_nop 0
	v_mov_b64_e32 v[22:23], v[228:229]
	v_lshlrev_b32_e32 v4, 16, v22
	v_and_b32_e32 v5, 0xffff0000, v22
	v_lshlrev_b32_e32 v6, 16, v23
	v_and_b32_e32 v7, 0xffff0000, v23
	v_pk_add_f32 v[2:3], v[2:3], v[6:7]
	v_pk_add_f32 v[4:5], v[0:1], v[4:5]
	v_mul_f32_e32 v1, v3, v3
	v_mul_f32_e32 v0, v5, v5
	v_fmac_f32_e32 v0, v4, v4
	v_fmac_f32_e32 v1, v2, v2
	v_add_f32_e32 v0, v0, v1
	v_add_f32_e32 v0, v8, v0
	ds_bpermute_b32 v1, v116, v0
	v_cvt_pk_bf16_f32 v238, v4, v5
	v_cvt_pk_bf16_f32 v239, v2, v3
	s_nop 1
	v_permlane16_swap_b32_e32 v236, v238
	v_permlane16_swap_b32_e32 v237, v239
	v_lshl_add_u64 v[242:243], v[18:19], 0, v[240:241]
	global_store_dwordx4 v[242:243], v[236:239], off offset:256 sc0 sc1
	s_waitcnt lgkmcnt(0)
	v_add_f32_e32 v0, v0, v1
	ds_bpermute_b32 v1, v114, v0
	s_and_saveexec_b64 s[28:29], s[4:5]
	s_cbranch_execz .LBB0_948
	s_waitcnt lgkmcnt(0)
	v_add_f32_e32 v2, v0, v1
	v_lshlrev_b64 v[0:1], 6, v[16:17]
	v_lshl_add_u64 v[0:1], s[60:61], 0, v[0:1]
	v_lshl_add_u64 v[0:1], s[26:27], 2, v[0:1]
	s_lshl_b32 s10, s44, 2
	v_lshl_add_u64 v[0:1], v[0:1], 0, s[10:11]
	global_store_dword v[0:1], v2, off

.LBB0_1606:
	v_lshl_add_u32 v144, s30, 8, v133
	s_lshl_b32 s12, s8, 8
	v_ashrrev_i32_e32 v145, 31, v144
	s_ashr_i32 s13, s12, 31
	v_lshlrev_b64 v[154:155], 11, v[144:145]
	v_mov_b32_e32 v143, s13
	v_or_b32_e32 v142, s12, v132
	v_lshl_add_u64 v[154:155], s[62:63], 0, v[154:155]
	v_lshl_add_u64 v[154:155], v[142:143], 1, v[154:155]
	global_load_dwordx2 v[164:165], v[154:155], off
	global_load_dwordx2 v[166:167], v[154:155], off offset:32
	global_load_dwordx2 v[168:169], v[154:155], off offset:256
	global_load_dwordx2 v[170:171], v[154:155], off offset:288
	v_add_co_u32_e32 v230, vcc, 0x8000, v154
	s_nop 1
	v_addc_co_u32_e32 v231, vcc, 0, v155, vcc
	global_load_dwordx2 v[172:173], v[230:231], off
	global_load_dwordx2 v[174:175], v[230:231], off offset:32
	global_load_dwordx2 v[176:177], v[230:231], off offset:256
	global_load_dwordx2 v[178:179], v[230:231], off offset:288
	v_add_co_u32_e32 v230, vcc, 0x10000, v154
	s_nop 1
	v_addc_co_u32_e32 v231, vcc, 0, v155, vcc
	global_load_dwordx2 v[180:181], v[230:231], off
	global_load_dwordx2 v[182:183], v[230:231], off offset:32
	global_load_dwordx2 v[184:185], v[230:231], off offset:256
	global_load_dwordx2 v[188:189], v[230:231], off offset:288
	v_add_co_u32_e32 v230, vcc, 0x18000, v154
	s_nop 1
	v_addc_co_u32_e32 v231, vcc, 0, v155, vcc
	global_load_dwordx2 v[190:191], v[230:231], off
	global_load_dwordx2 v[192:193], v[230:231], off offset:32
	global_load_dwordx2 v[194:195], v[230:231], off offset:256
	global_load_dwordx2 v[196:197], v[230:231], off offset:288
	v_add_co_u32_e32 v230, vcc, 0x40000, v154
	s_nop 1
	v_addc_co_u32_e32 v231, vcc, 0, v155, vcc
	global_load_dwordx2 v[198:199], v[230:231], off
	global_load_dwordx2 v[200:201], v[230:231], off offset:32
	global_load_dwordx2 v[202:203], v[230:231], off offset:256
	global_load_dwordx2 v[204:205], v[230:231], off offset:288
	v_add_co_u32_e32 v230, vcc, 0x48000, v154
	s_nop 1
	v_addc_co_u32_e32 v231, vcc, 0, v155, vcc
	global_load_dwordx2 v[206:207], v[230:231], off
	global_load_dwordx2 v[208:209], v[230:231], off offset:32
	global_load_dwordx2 v[210:211], v[230:231], off offset:256
	global_load_dwordx2 v[212:213], v[230:231], off offset:288
	v_add_co_u32_e32 v230, vcc, 0x50000, v154
	s_nop 1
	v_addc_co_u32_e32 v231, vcc, 0, v155, vcc
	global_load_dwordx2 v[214:215], v[230:231], off
	global_load_dwordx2 v[216:217], v[230:231], off offset:32
	global_load_dwordx2 v[218:219], v[230:231], off offset:256
	global_load_dwordx2 v[220:221], v[230:231], off offset:288
	v_add_co_u32_e32 v230, vcc, 0x58000, v154
	s_nop 1
	v_addc_co_u32_e32 v231, vcc, 0, v155, vcc
	global_load_dwordx2 v[222:223], v[230:231], off
	global_load_dwordx2 v[224:225], v[230:231], off offset:32
	global_load_dwordx2 v[226:227], v[230:231], off offset:256
	global_load_dwordx2 v[228:229], v[230:231], off offset:288
	s_waitcnt vmcnt(0)
	v_mbcnt_lo_u32_b32 v240, -1, 0
	v_mbcnt_hi_u32_b32 v240, -1, v240
	v_and_b32_e32 v240, 16, v240
	v_lshrrev_b32_e32 v241, 1, v240
	v_add_u32_e32 v240, v240, v241
	v_mov_b32_e32 v241, 0
	s_lshl_b32 s30, s8, 2
	s_ashr_i32 s31, s30, 31
	v_mov_b64_e32 v[156:157], v[164:165]
	v_lshlrev_b32_e32 v158, 16, v156
	v_and_b32_e32 v159, 0xffff0000, v156
	v_lshlrev_b32_e32 v156, 16, v157
	v_and_b32_e32 v157, 0xffff0000, v157
	v_pk_add_f32 v[126:127], v[126:127], v[156:157]
	v_pk_add_f32 v[124:125], v[124:125], v[158:159]
	s_nop 0
	v_cvt_pk_bf16_f32 v232, v124, v125
	v_cvt_pk_bf16_f32 v233, v126, v127
	v_mul_f32_e32 v125, v125, v125
	s_nop 0
	v_mul_f32_e32 v127, v127, v127
	v_fmac_f32_e32 v125, v124, v124
	v_fmac_f32_e32 v127, v126, v126
	v_add_f32_e32 v124, v125, v127
	v_mov_b64_e32 v[158:159], v[166:167]
	v_lshlrev_b32_e32 v156, 16, v158
	v_and_b32_e32 v157, 0xffff0000, v158
	v_lshlrev_b32_e32 v158, 16, v159
	v_and_b32_e32 v159, 0xffff0000, v159
	v_pk_add_f32 v[122:123], v[122:123], v[158:159]
	v_pk_add_f32 v[120:121], v[120:121], v[156:157]
	s_nop 0
	v_cvt_pk_bf16_f32 v234, v120, v121
	v_cvt_pk_bf16_f32 v235, v122, v123
	v_mul_f32_e32 v121, v121, v121
	s_nop 1
	v_permlane16_swap_b32_e32 v232, v234
	v_permlane16_swap_b32_e32 v233, v235
	v_lshl_add_u64 v[242:243], v[154:155], 0, v[240:241]
	global_store_dwordx4 v[242:243], v[232:235], off sc0 sc1
	v_mul_f32_e32 v123, v123, v123
	v_fmac_f32_e32 v121, v120, v120
	v_fmac_f32_e32 v123, v122, v122
	v_add_f32_e32 v120, v121, v123
	v_add_f32_e32 v120, v124, v120
	v_mov_b64_e32 v[158:159], v[168:169]
	v_lshlrev_b32_e32 v156, 16, v158
	v_and_b32_e32 v157, 0xffff0000, v158
	v_lshlrev_b32_e32 v158, 16, v159
	v_and_b32_e32 v159, 0xffff0000, v159
	v_pk_add_f32 v[118:119], v[118:119], v[158:159]
	v_pk_add_f32 v[116:117], v[116:117], v[156:157]
	s_nop 0
	v_cvt_pk_bf16_f32 v236, v116, v117
	v_cvt_pk_bf16_f32 v237, v118, v119
	v_mul_f32_e32 v117, v117, v117
	v_mul_f32_e32 v119, v119, v119
	v_fmac_f32_e32 v117, v116, v116
	v_fmac_f32_e32 v119, v118, v118
	v_add_f32_e32 v116, v117, v119
	v_add_f32_e32 v120, v120, v116
	s_nop 0
	v_mov_b64_e32 v[158:159], v[170:171]
	v_lshlrev_b32_e32 v116, 16, v158
	v_and_b32_e32 v117, 0xffff0000, v158
	v_lshlrev_b32_e32 v118, 16, v159
	v_and_b32_e32 v119, 0xffff0000, v159
	v_pk_add_f32 v[114:115], v[114:115], v[118:119]
	v_pk_add_f32 v[116:117], v[112:113], v[116:117]
	v_mul_f32_e32 v113, v115, v115
	v_mul_f32_e32 v112, v117, v117
	v_fmac_f32_e32 v112, v116, v116
	v_fmac_f32_e32 v113, v114, v114
	v_add_f32_e32 v112, v112, v113
	v_add_f32_e32 v112, v120, v112
	ds_bpermute_b32 v113, v149, v112
	v_cvt_pk_bf16_f32 v238, v116, v117
	v_cvt_pk_bf16_f32 v239, v114, v115
	s_nop 1
	v_permlane16_swap_b32_e32 v236, v238
	v_permlane16_swap_b32_e32 v237, v239
	v_lshl_add_u64 v[242:243], v[154:155], 0, v[240:241]
	global_store_dwordx4 v[242:243], v[236:239], off offset:256 sc0 sc1
	s_waitcnt lgkmcnt(0)
	v_add_f32_e32 v112, v112, v113
	ds_bpermute_b32 v113, v153, v112
	s_and_saveexec_b64 s[36:37], s[4:5]
	s_cbranch_execz .LBB0_1608
	s_waitcnt lgkmcnt(0)
	v_add_f32_e32 v114, v112, v113
	v_lshlrev_b64 v[112:113], 6, v[144:145]
	v_lshl_add_u64 v[112:113], s[60:61], 0, v[112:113]
	v_lshl_add_u64 v[112:113], s[30:31], 2, v[112:113]
	s_lshl_b32 s8, s50, 2
	v_lshl_add_u64 v[112:113], v[112:113], 0, s[8:9]
	global_store_dword v[112:113], v114, off
.LBB0_1608:
	s_or_b64 exec, exec, s[36:37]
	v_or_b32_e32 v112, 16, v144
	s_waitcnt lgkmcnt(0)
	v_ashrrev_i32_e32 v113, 31, v112
	v_lshlrev_b64 v[114:115], 11, v[112:113]
	v_lshl_add_u64 v[114:115], s[62:63], 0, v[114:115]
	v_lshl_add_u64 v[114:115], v[142:143], 1, v[114:115]
	v_mov_b64_e32 v[116:117], v[172:173]
	v_lshlrev_b32_e32 v118, 16, v116
	v_and_b32_e32 v119, 0xffff0000, v116
	v_lshlrev_b32_e32 v116, 16, v117
	v_and_b32_e32 v117, 0xffff0000, v117
	v_pk_add_f32 v[110:111], v[110:111], v[116:117]
	v_pk_add_f32 v[108:109], v[108:109], v[118:119]
	s_nop 0
	v_cvt_pk_bf16_f32 v232, v108, v109
	v_cvt_pk_bf16_f32 v233, v110, v111
	v_mul_f32_e32 v109, v109, v109
	s_nop 0
	v_mul_f32_e32 v111, v111, v111
	v_fmac_f32_e32 v109, v108, v108
	v_fmac_f32_e32 v111, v110, v110
	v_add_f32_e32 v108, v109, v111
	v_mov_b64_e32 v[118:119], v[174:175]
	v_lshlrev_b32_e32 v116, 16, v118
	v_and_b32_e32 v117, 0xffff0000, v118
	v_lshlrev_b32_e32 v118, 16, v119
	v_and_b32_e32 v119, 0xffff0000, v119
	v_pk_add_f32 v[106:107], v[106:107], v[118:119]
	v_pk_add_f32 v[104:105], v[104:105], v[116:117]
	s_nop 0
	v_cvt_pk_bf16_f32 v234, v104, v105
	v_cvt_pk_bf16_f32 v235, v106, v107
	v_mul_f32_e32 v105, v105, v105
	s_nop 1
	v_permlane16_swap_b32_e32 v232, v234
	v_permlane16_swap_b32_e32 v233, v235
	v_lshl_add_u64 v[242:243], v[114:115], 0, v[240:241]
	global_store_dwordx4 v[242:243], v[232:235], off sc0 sc1
	v_mul_f32_e32 v107, v107, v107
	v_fmac_f32_e32 v105, v104, v104
	v_fmac_f32_e32 v107, v106, v106
	v_add_f32_e32 v104, v105, v107
	v_add_f32_e32 v104, v108, v104
	v_mov_b64_e32 v[118:119], v[176:177]
	v_lshlrev_b32_e32 v116, 16, v118
	v_and_b32_e32 v117, 0xffff0000, v118
	v_lshlrev_b32_e32 v118, 16, v119
	v_and_b32_e32 v119, 0xffff0000, v119
	v_pk_add_f32 v[102:103], v[102:103], v[118:119]
	v_pk_add_f32 v[100:101], v[100:101], v[116:117]
	s_nop 0
	v_cvt_pk_bf16_f32 v236, v100, v101
	v_cvt_pk_bf16_f32 v237, v102, v103
	v_mul_f32_e32 v101, v101, v101
	v_mul_f32_e32 v103, v103, v103
	v_fmac_f32_e32 v101, v100, v100
	v_fmac_f32_e32 v103, v102, v102
	v_add_f32_e32 v100, v101, v103
	v_add_f32_e32 v104, v104, v100
	s_nop 0
	v_mov_b64_e32 v[118:119], v[178:179]
	v_lshlrev_b32_e32 v100, 16, v118
	v_and_b32_e32 v101, 0xffff0000, v118
	v_lshlrev_b32_e32 v102, 16, v119
	v_and_b32_e32 v103, 0xffff0000, v119
	v_pk_add_f32 v[98:99], v[98:99], v[102:103]
	v_pk_add_f32 v[100:101], v[96:97], v[100:101]
	v_mul_f32_e32 v97, v99, v99
	v_mul_f32_e32 v96, v101, v101
	v_fmac_f32_e32 v96, v100, v100
	v_fmac_f32_e32 v97, v98, v98
	v_add_f32_e32 v96, v96, v97
	v_add_f32_e32 v96, v104, v96
	ds_bpermute_b32 v97, v149, v96
	v_cvt_pk_bf16_f32 v238, v100, v101
	v_cvt_pk_bf16_f32 v239, v98, v99
	s_nop 1
	v_permlane16_swap_b32_e32 v236, v238
	v_permlane16_swap_b32_e32 v237, v239
	v_lshl_add_u64 v[242:243], v[114:115], 0, v[240:241]
	global_store_dwordx4 v[242:243], v[236:239], off offset:256 sc0 sc1
	s_waitcnt lgkmcnt(0)
	v_add_f32_e32 v96, v96, v97
	ds_bpermute_b32 v97, v153, v96
	s_and_saveexec_b64 s[36:37], s[4:5]
	s_cbranch_execz .LBB0_1610
	s_waitcnt lgkmcnt(0)
	v_add_f32_e32 v98, v96, v97
	v_lshlrev_b64 v[96:97], 6, v[112:113]
	v_lshl_add_u64 v[96:97], s[60:61], 0, v[96:97]
	v_lshl_add_u64 v[96:97], s[30:31], 2, v[96:97]
	s_lshl_b32 s8, s50, 2
	v_lshl_add_u64 v[96:97], v[96:97], 0, s[8:9]
	global_store_dword v[96:97], v98, off
.LBB0_1610:
	s_or_b64 exec, exec, s[36:37]
	v_or_b32_e32 v96, 32, v144
	s_waitcnt lgkmcnt(0)
	v_ashrrev_i32_e32 v97, 31, v96
	v_lshlrev_b64 v[98:99], 11, v[96:97]
	v_lshl_add_u64 v[98:99], s[62:63], 0, v[98:99]
	v_lshl_add_u64 v[98:99], v[142:143], 1, v[98:99]
	v_mov_b64_e32 v[100:101], v[180:181]
	v_lshlrev_b32_e32 v102, 16, v100
	v_and_b32_e32 v103, 0xffff0000, v100
	v_lshlrev_b32_e32 v100, 16, v101
	v_and_b32_e32 v101, 0xffff0000, v101
	v_pk_add_f32 v[94:95], v[94:95], v[100:101]
	v_pk_add_f32 v[92:93], v[92:93], v[102:103]
	s_nop 0
	v_cvt_pk_bf16_f32 v232, v92, v93
	v_cvt_pk_bf16_f32 v233, v94, v95
	v_mul_f32_e32 v93, v93, v93
	s_nop 0
	v_mul_f32_e32 v95, v95, v95
	v_fmac_f32_e32 v93, v92, v92
	v_fmac_f32_e32 v95, v94, v94
	v_add_f32_e32 v92, v93, v95
	v_mov_b64_e32 v[102:103], v[182:183]
	v_lshlrev_b32_e32 v100, 16, v102
	v_and_b32_e32 v101, 0xffff0000, v102
	v_lshlrev_b32_e32 v102, 16, v103
	v_and_b32_e32 v103, 0xffff0000, v103
	v_pk_add_f32 v[90:91], v[90:91], v[102:103]
	v_pk_add_f32 v[88:89], v[88:89], v[100:101]
	s_nop 0
	v_cvt_pk_bf16_f32 v234, v88, v89
	v_cvt_pk_bf16_f32 v235, v90, v91
	v_mul_f32_e32 v89, v89, v89
	s_nop 1
	v_permlane16_swap_b32_e32 v232, v234
	v_permlane16_swap_b32_e32 v233, v235
	v_lshl_add_u64 v[242:243], v[98:99], 0, v[240:241]
	global_store_dwordx4 v[242:243], v[232:235], off sc0 sc1
	v_mul_f32_e32 v91, v91, v91
	v_fmac_f32_e32 v89, v88, v88
	v_fmac_f32_e32 v91, v90, v90
	v_add_f32_e32 v88, v89, v91
	v_add_f32_e32 v88, v92, v88
	v_mov_b64_e32 v[102:103], v[184:185]
	v_lshlrev_b32_e32 v100, 16, v102
	v_and_b32_e32 v101, 0xffff0000, v102
	v_lshlrev_b32_e32 v102, 16, v103
	v_and_b32_e32 v103, 0xffff0000, v103
	v_pk_add_f32 v[86:87], v[86:87], v[102:103]
	v_pk_add_f32 v[84:85], v[84:85], v[100:101]
	s_nop 0
	v_cvt_pk_bf16_f32 v236, v84, v85
	v_cvt_pk_bf16_f32 v237, v86, v87
	v_mul_f32_e32 v85, v85, v85
	v_mul_f32_e32 v87, v87, v87
	v_fmac_f32_e32 v85, v84, v84
	v_fmac_f32_e32 v87, v86, v86
	v_add_f32_e32 v84, v85, v87
	v_add_f32_e32 v88, v88, v84
	s_nop 0
	v_mov_b64_e32 v[102:103], v[188:189]
	v_lshlrev_b32_e32 v84, 16, v102
	v_and_b32_e32 v85, 0xffff0000, v102
	v_lshlrev_b32_e32 v86, 16, v103
	v_and_b32_e32 v87, 0xffff0000, v103
	v_pk_add_f32 v[82:83], v[82:83], v[86:87]
	v_pk_add_f32 v[84:85], v[80:81], v[84:85]
	v_mul_f32_e32 v81, v83, v83
	v_mul_f32_e32 v80, v85, v85
	v_fmac_f32_e32 v80, v84, v84
	v_fmac_f32_e32 v81, v82, v82
	v_add_f32_e32 v80, v80, v81
	v_add_f32_e32 v80, v88, v80
	ds_bpermute_b32 v81, v149, v80
	v_cvt_pk_bf16_f32 v238, v84, v85
	v_cvt_pk_bf16_f32 v239, v82, v83
	s_nop 1
	v_permlane16_swap_b32_e32 v236, v238
	v_permlane16_swap_b32_e32 v237, v239
	v_lshl_add_u64 v[242:243], v[98:99], 0, v[240:241]
	global_store_dwordx4 v[242:243], v[236:239], off offset:256 sc0 sc1
	s_waitcnt lgkmcnt(0)
	v_add_f32_e32 v80, v80, v81
	ds_bpermute_b32 v81, v153, v80
	s_and_saveexec_b64 s[36:37], s[4:5]
	s_cbranch_execz .LBB0_1612
	s_waitcnt lgkmcnt(0)
	v_add_f32_e32 v82, v80, v81
	v_lshlrev_b64 v[80:81], 6, v[96:97]
	v_lshl_add_u64 v[80:81], s[60:61], 0, v[80:81]
	v_lshl_add_u64 v[80:81], s[30:31], 2, v[80:81]
	s_lshl_b32 s8, s50, 2
	v_lshl_add_u64 v[80:81], v[80:81], 0, s[8:9]
	global_store_dword v[80:81], v82, off
.LBB0_1612:
	s_or_b64 exec, exec, s[36:37]
	v_or_b32_e32 v80, 48, v144
	s_waitcnt lgkmcnt(0)
	v_ashrrev_i32_e32 v81, 31, v80
	v_lshlrev_b64 v[82:83], 11, v[80:81]
	v_lshl_add_u64 v[82:83], s[62:63], 0, v[82:83]
	v_lshl_add_u64 v[82:83], v[142:143], 1, v[82:83]
	v_mov_b64_e32 v[84:85], v[190:191]
	v_lshlrev_b32_e32 v86, 16, v84
	v_and_b32_e32 v87, 0xffff0000, v84
	v_lshlrev_b32_e32 v84, 16, v85
	v_and_b32_e32 v85, 0xffff0000, v85
	v_pk_add_f32 v[78:79], v[78:79], v[84:85]
	v_pk_add_f32 v[76:77], v[76:77], v[86:87]
	s_nop 0
	v_cvt_pk_bf16_f32 v232, v76, v77
	v_cvt_pk_bf16_f32 v233, v78, v79
	v_mul_f32_e32 v77, v77, v77
	s_nop 0
	v_mul_f32_e32 v79, v79, v79
	v_fmac_f32_e32 v77, v76, v76
	v_fmac_f32_e32 v79, v78, v78
	v_add_f32_e32 v76, v77, v79
	v_mov_b64_e32 v[86:87], v[192:193]
	v_lshlrev_b32_e32 v84, 16, v86
	v_and_b32_e32 v85, 0xffff0000, v86
	v_lshlrev_b32_e32 v86, 16, v87
	v_and_b32_e32 v87, 0xffff0000, v87
	v_pk_add_f32 v[74:75], v[74:75], v[86:87]
	v_pk_add_f32 v[72:73], v[72:73], v[84:85]
	s_nop 0
	v_cvt_pk_bf16_f32 v234, v72, v73
	v_cvt_pk_bf16_f32 v235, v74, v75
	v_mul_f32_e32 v73, v73, v73
	s_nop 1
	v_permlane16_swap_b32_e32 v232, v234
	v_permlane16_swap_b32_e32 v233, v235
	v_lshl_add_u64 v[242:243], v[82:83], 0, v[240:241]
	global_store_dwordx4 v[242:243], v[232:235], off sc0 sc1
	v_mul_f32_e32 v75, v75, v75
	v_fmac_f32_e32 v73, v72, v72
	v_fmac_f32_e32 v75, v74, v74
	v_add_f32_e32 v72, v73, v75
	v_add_f32_e32 v72, v76, v72
	v_mov_b64_e32 v[86:87], v[194:195]
	v_lshlrev_b32_e32 v84, 16, v86
	v_and_b32_e32 v85, 0xffff0000, v86
	v_lshlrev_b32_e32 v86, 16, v87
	v_and_b32_e32 v87, 0xffff0000, v87
	v_pk_add_f32 v[70:71], v[70:71], v[86:87]
	v_pk_add_f32 v[68:69], v[68:69], v[84:85]
	s_nop 0
	v_cvt_pk_bf16_f32 v236, v68, v69
	v_cvt_pk_bf16_f32 v237, v70, v71
	v_mul_f32_e32 v69, v69, v69
	v_mul_f32_e32 v71, v71, v71
	v_fmac_f32_e32 v69, v68, v68
	v_fmac_f32_e32 v71, v70, v70
	v_add_f32_e32 v68, v69, v71
	v_add_f32_e32 v72, v72, v68
	s_nop 0
	v_mov_b64_e32 v[86:87], v[196:197]
	v_lshlrev_b32_e32 v68, 16, v86
	v_and_b32_e32 v69, 0xffff0000, v86
	v_lshlrev_b32_e32 v70, 16, v87
	v_and_b32_e32 v71, 0xffff0000, v87
	v_pk_add_f32 v[66:67], v[66:67], v[70:71]
	v_pk_add_f32 v[68:69], v[64:65], v[68:69]
	v_mul_f32_e32 v65, v67, v67
	v_mul_f32_e32 v64, v69, v69
	v_fmac_f32_e32 v64, v68, v68
	v_fmac_f32_e32 v65, v66, v66
	v_add_f32_e32 v64, v64, v65
	v_add_f32_e32 v64, v72, v64
	ds_bpermute_b32 v65, v149, v64
	v_cvt_pk_bf16_f32 v238, v68, v69
	v_cvt_pk_bf16_f32 v239, v66, v67
	s_nop 1
	v_permlane16_swap_b32_e32 v236, v238
	v_permlane16_swap_b32_e32 v237, v239
	v_lshl_add_u64 v[242:243], v[82:83], 0, v[240:241]
	global_store_dwordx4 v[242:243], v[236:239], off offset:256 sc0 sc1
	s_waitcnt lgkmcnt(0)
	v_add_f32_e32 v64, v64, v65
	ds_bpermute_b32 v65, v153, v64
	s_and_saveexec_b64 s[36:37], s[4:5]
	s_cbranch_execz .LBB0_1614
	s_waitcnt lgkmcnt(0)
	v_add_f32_e32 v66, v64, v65
	v_lshlrev_b64 v[64:65], 6, v[80:81]
	v_lshl_add_u64 v[64:65], s[60:61], 0, v[64:65]
	v_lshl_add_u64 v[64:65], s[30:31], 2, v[64:65]
	s_lshl_b32 s8, s50, 2
	v_lshl_add_u64 v[64:65], v[64:65], 0, s[8:9]
	global_store_dword v[64:65], v66, off
.LBB0_1614:
	s_or_b64 exec, exec, s[36:37]
	v_add_u32_e32 v64, 0x80, v144
	s_waitcnt lgkmcnt(0)
	v_ashrrev_i32_e32 v65, 31, v64
	v_lshlrev_b64 v[66:67], 11, v[64:65]
	v_lshl_add_u64 v[66:67], s[62:63], 0, v[66:67]
	v_lshl_add_u64 v[66:67], v[142:143], 1, v[66:67]
	v_mov_b64_e32 v[68:69], v[198:199]
	v_lshlrev_b32_e32 v70, 16, v68
	v_and_b32_e32 v71, 0xffff0000, v68
	v_lshlrev_b32_e32 v68, 16, v69
	v_and_b32_e32 v69, 0xffff0000, v69
	v_pk_add_f32 v[62:63], v[62:63], v[68:69]
	v_pk_add_f32 v[60:61], v[60:61], v[70:71]
	s_nop 0
	v_cvt_pk_bf16_f32 v232, v60, v61
	v_cvt_pk_bf16_f32 v233, v62, v63
	v_mul_f32_e32 v61, v61, v61
	s_nop 0
	v_mul_f32_e32 v63, v63, v63
	v_fmac_f32_e32 v61, v60, v60
	v_fmac_f32_e32 v63, v62, v62
	v_add_f32_e32 v60, v61, v63
	v_mov_b64_e32 v[70:71], v[200:201]
	v_lshlrev_b32_e32 v68, 16, v70
	v_and_b32_e32 v69, 0xffff0000, v70
	v_lshlrev_b32_e32 v70, 16, v71
	v_and_b32_e32 v71, 0xffff0000, v71
	v_pk_add_f32 v[58:59], v[58:59], v[70:71]
	v_pk_add_f32 v[56:57], v[56:57], v[68:69]
	s_nop 0
	v_cvt_pk_bf16_f32 v234, v56, v57
	v_cvt_pk_bf16_f32 v235, v58, v59
	v_mul_f32_e32 v57, v57, v57
	s_nop 1
	v_permlane16_swap_b32_e32 v232, v234
	v_permlane16_swap_b32_e32 v233, v235
	v_lshl_add_u64 v[242:243], v[66:67], 0, v[240:241]
	global_store_dwordx4 v[242:243], v[232:235], off sc0 sc1
	v_mul_f32_e32 v59, v59, v59
	v_fmac_f32_e32 v57, v56, v56
	v_fmac_f32_e32 v59, v58, v58
	v_add_f32_e32 v56, v57, v59
	v_add_f32_e32 v56, v60, v56
	v_mov_b64_e32 v[70:71], v[202:203]
	v_lshlrev_b32_e32 v68, 16, v70
	v_and_b32_e32 v69, 0xffff0000, v70
	v_lshlrev_b32_e32 v70, 16, v71
	v_and_b32_e32 v71, 0xffff0000, v71
	v_pk_add_f32 v[54:55], v[54:55], v[70:71]
	v_pk_add_f32 v[52:53], v[52:53], v[68:69]
	s_nop 0
	v_cvt_pk_bf16_f32 v236, v52, v53
	v_cvt_pk_bf16_f32 v237, v54, v55
	v_mul_f32_e32 v53, v53, v53
	v_mul_f32_e32 v55, v55, v55
	v_fmac_f32_e32 v53, v52, v52
	v_fmac_f32_e32 v55, v54, v54
	v_add_f32_e32 v52, v53, v55
	v_add_f32_e32 v56, v56, v52
	s_nop 0
	v_mov_b64_e32 v[70:71], v[204:205]
	v_lshlrev_b32_e32 v52, 16, v70
	v_and_b32_e32 v53, 0xffff0000, v70
	v_lshlrev_b32_e32 v54, 16, v71
	v_and_b32_e32 v55, 0xffff0000, v71
	v_pk_add_f32 v[50:51], v[50:51], v[54:55]
	v_pk_add_f32 v[52:53], v[48:49], v[52:53]
	v_mul_f32_e32 v49, v51, v51
	v_mul_f32_e32 v48, v53, v53
	v_fmac_f32_e32 v48, v52, v52
	v_fmac_f32_e32 v49, v50, v50
	v_add_f32_e32 v48, v48, v49
	v_add_f32_e32 v48, v56, v48
	ds_bpermute_b32 v49, v149, v48
	v_cvt_pk_bf16_f32 v238, v52, v53
	v_cvt_pk_bf16_f32 v239, v50, v51
	s_nop 1
	v_permlane16_swap_b32_e32 v236, v238
	v_permlane16_swap_b32_e32 v237, v239
	v_lshl_add_u64 v[242:243], v[66:67], 0, v[240:241]
	global_store_dwordx4 v[242:243], v[236:239], off offset:256 sc0 sc1
	s_waitcnt lgkmcnt(0)
	v_add_f32_e32 v48, v48, v49
	ds_bpermute_b32 v49, v153, v48
	s_and_saveexec_b64 s[36:37], s[4:5]
	s_cbranch_execz .LBB0_1616
	s_waitcnt lgkmcnt(0)
	v_add_f32_e32 v50, v48, v49
	v_lshlrev_b64 v[48:49], 6, v[64:65]
	v_lshl_add_u64 v[48:49], s[60:61], 0, v[48:49]
	v_lshl_add_u64 v[48:49], s[30:31], 2, v[48:49]
	s_lshl_b32 s8, s50, 2
	v_lshl_add_u64 v[48:49], v[48:49], 0, s[8:9]
	global_store_dword v[48:49], v50, off
.LBB0_1616:
	s_or_b64 exec, exec, s[36:37]
	v_add_u32_e32 v48, 0x90, v144
	s_waitcnt lgkmcnt(0)
	v_ashrrev_i32_e32 v49, 31, v48
	v_lshlrev_b64 v[50:51], 11, v[48:49]
	v_lshl_add_u64 v[50:51], s[62:63], 0, v[50:51]
	v_lshl_add_u64 v[50:51], v[142:143], 1, v[50:51]
	v_mov_b64_e32 v[52:53], v[206:207]
	v_lshlrev_b32_e32 v54, 16, v52
	v_and_b32_e32 v55, 0xffff0000, v52
	v_lshlrev_b32_e32 v52, 16, v53
	v_and_b32_e32 v53, 0xffff0000, v53
	v_pk_add_f32 v[46:47], v[46:47], v[52:53]
	v_pk_add_f32 v[44:45], v[44:45], v[54:55]
	s_nop 0
	v_cvt_pk_bf16_f32 v232, v44, v45
	v_cvt_pk_bf16_f32 v233, v46, v47
	v_mul_f32_e32 v45, v45, v45
	s_nop 0
	v_mul_f32_e32 v47, v47, v47
	v_fmac_f32_e32 v45, v44, v44
	v_fmac_f32_e32 v47, v46, v46
	v_add_f32_e32 v44, v45, v47
	v_mov_b64_e32 v[54:55], v[208:209]
	v_lshlrev_b32_e32 v52, 16, v54
	v_and_b32_e32 v53, 0xffff0000, v54
	v_lshlrev_b32_e32 v54, 16, v55
	v_and_b32_e32 v55, 0xffff0000, v55
	v_pk_add_f32 v[42:43], v[42:43], v[54:55]
	v_pk_add_f32 v[40:41], v[40:41], v[52:53]
	s_nop 0
	v_cvt_pk_bf16_f32 v234, v40, v41
	v_cvt_pk_bf16_f32 v235, v42, v43
	v_mul_f32_e32 v41, v41, v41
	s_nop 1
	v_permlane16_swap_b32_e32 v232, v234
	v_permlane16_swap_b32_e32 v233, v235
	v_lshl_add_u64 v[242:243], v[50:51], 0, v[240:241]
	global_store_dwordx4 v[242:243], v[232:235], off sc0 sc1
	v_mul_f32_e32 v43, v43, v43
	v_fmac_f32_e32 v41, v40, v40
	v_fmac_f32_e32 v43, v42, v42
	v_add_f32_e32 v40, v41, v43
	v_add_f32_e32 v40, v44, v40
	v_mov_b64_e32 v[54:55], v[210:211]
	v_lshlrev_b32_e32 v52, 16, v54
	v_and_b32_e32 v53, 0xffff0000, v54
	v_lshlrev_b32_e32 v54, 16, v55
	v_and_b32_e32 v55, 0xffff0000, v55
	v_pk_add_f32 v[38:39], v[38:39], v[54:55]
	v_pk_add_f32 v[36:37], v[36:37], v[52:53]
	s_nop 0
	v_cvt_pk_bf16_f32 v236, v36, v37
	v_cvt_pk_bf16_f32 v237, v38, v39
	v_mul_f32_e32 v37, v37, v37
	v_mul_f32_e32 v39, v39, v39
	v_fmac_f32_e32 v37, v36, v36
	v_fmac_f32_e32 v39, v38, v38
	v_add_f32_e32 v36, v37, v39
	v_add_f32_e32 v40, v40, v36
	s_nop 0
	v_mov_b64_e32 v[54:55], v[212:213]
	v_lshlrev_b32_e32 v36, 16, v54
	v_and_b32_e32 v37, 0xffff0000, v54
	v_lshlrev_b32_e32 v38, 16, v55
	v_and_b32_e32 v39, 0xffff0000, v55
	v_pk_add_f32 v[34:35], v[34:35], v[38:39]
	v_pk_add_f32 v[36:37], v[32:33], v[36:37]
	v_mul_f32_e32 v33, v35, v35
	v_mul_f32_e32 v32, v37, v37
	v_fmac_f32_e32 v32, v36, v36
	v_fmac_f32_e32 v33, v34, v34
	v_add_f32_e32 v32, v32, v33
	v_add_f32_e32 v32, v40, v32
	ds_bpermute_b32 v33, v149, v32
	v_cvt_pk_bf16_f32 v238, v36, v37
	v_cvt_pk_bf16_f32 v239, v34, v35
	s_nop 1
	v_permlane16_swap_b32_e32 v236, v238
	v_permlane16_swap_b32_e32 v237, v239
	v_lshl_add_u64 v[242:243], v[50:51], 0, v[240:241]
	global_store_dwordx4 v[242:243], v[236:239], off offset:256 sc0 sc1
	s_waitcnt lgkmcnt(0)
	v_add_f32_e32 v32, v32, v33
	ds_bpermute_b32 v33, v153, v32
	s_and_saveexec_b64 s[36:37], s[4:5]
	s_cbranch_execz .LBB0_1618
	s_waitcnt lgkmcnt(0)
	v_add_f32_e32 v34, v32, v33
	v_lshlrev_b64 v[32:33], 6, v[48:49]
	v_lshl_add_u64 v[32:33], s[60:61], 0, v[32:33]
	v_lshl_add_u64 v[32:33], s[30:31], 2, v[32:33]
	s_lshl_b32 s8, s50, 2
	v_lshl_add_u64 v[32:33], v[32:33], 0, s[8:9]
	global_store_dword v[32:33], v34, off
.LBB0_1618:
	s_or_b64 exec, exec, s[36:37]
	v_add_u32_e32 v32, 0xa0, v144
	s_waitcnt lgkmcnt(0)
	v_ashrrev_i32_e32 v33, 31, v32
	v_lshlrev_b64 v[34:35], 11, v[32:33]
	v_lshl_add_u64 v[34:35], s[62:63], 0, v[34:35]
	v_lshl_add_u64 v[34:35], v[142:143], 1, v[34:35]
	v_mov_b64_e32 v[36:37], v[214:215]
	v_lshlrev_b32_e32 v38, 16, v36
	v_and_b32_e32 v39, 0xffff0000, v36
	v_lshlrev_b32_e32 v36, 16, v37
	v_and_b32_e32 v37, 0xffff0000, v37
	v_pk_add_f32 v[30:31], v[30:31], v[36:37]
	v_pk_add_f32 v[28:29], v[28:29], v[38:39]
	s_nop 0
	v_cvt_pk_bf16_f32 v232, v28, v29
	v_cvt_pk_bf16_f32 v233, v30, v31
	v_mul_f32_e32 v29, v29, v29
	s_nop 0
	v_mul_f32_e32 v31, v31, v31
	v_fmac_f32_e32 v29, v28, v28
	v_fmac_f32_e32 v31, v30, v30
	v_add_f32_e32 v28, v29, v31
	v_mov_b64_e32 v[38:39], v[216:217]
	v_lshlrev_b32_e32 v36, 16, v38
	v_and_b32_e32 v37, 0xffff0000, v38
	v_lshlrev_b32_e32 v38, 16, v39
	v_and_b32_e32 v39, 0xffff0000, v39
	v_pk_add_f32 v[26:27], v[26:27], v[38:39]
	v_pk_add_f32 v[24:25], v[24:25], v[36:37]
	s_nop 0
	v_cvt_pk_bf16_f32 v234, v24, v25
	v_cvt_pk_bf16_f32 v235, v26, v27
	v_mul_f32_e32 v25, v25, v25
	s_nop 1
	v_permlane16_swap_b32_e32 v232, v234
	v_permlane16_swap_b32_e32 v233, v235
	v_lshl_add_u64 v[242:243], v[34:35], 0, v[240:241]
	global_store_dwordx4 v[242:243], v[232:235], off sc0 sc1
	v_mul_f32_e32 v27, v27, v27
	v_fmac_f32_e32 v25, v24, v24
	v_fmac_f32_e32 v27, v26, v26
	v_add_f32_e32 v24, v25, v27
	v_add_f32_e32 v24, v28, v24
	v_mov_b64_e32 v[38:39], v[218:219]
	v_lshlrev_b32_e32 v36, 16, v38
	v_and_b32_e32 v37, 0xffff0000, v38
	v_lshlrev_b32_e32 v38, 16, v39
	v_and_b32_e32 v39, 0xffff0000, v39
	v_pk_add_f32 v[22:23], v[22:23], v[38:39]
	v_pk_add_f32 v[20:21], v[20:21], v[36:37]
	s_nop 0
	v_cvt_pk_bf16_f32 v236, v20, v21
	v_cvt_pk_bf16_f32 v237, v22, v23
	v_mul_f32_e32 v21, v21, v21
	v_mul_f32_e32 v23, v23, v23
	v_fmac_f32_e32 v21, v20, v20
	v_fmac_f32_e32 v23, v22, v22
	v_add_f32_e32 v20, v21, v23
	v_add_f32_e32 v24, v24, v20
	s_nop 0
	v_mov_b64_e32 v[38:39], v[220:221]
	v_lshlrev_b32_e32 v20, 16, v38
	v_and_b32_e32 v21, 0xffff0000, v38
	v_lshlrev_b32_e32 v22, 16, v39
	v_and_b32_e32 v23, 0xffff0000, v39
	v_pk_add_f32 v[18:19], v[18:19], v[22:23]
	v_pk_add_f32 v[20:21], v[16:17], v[20:21]
	v_mul_f32_e32 v17, v19, v19
	v_mul_f32_e32 v16, v21, v21
	v_fmac_f32_e32 v16, v20, v20
	v_fmac_f32_e32 v17, v18, v18
	v_add_f32_e32 v16, v16, v17
	v_add_f32_e32 v16, v24, v16
	ds_bpermute_b32 v17, v149, v16
	v_cvt_pk_bf16_f32 v238, v20, v21
	v_cvt_pk_bf16_f32 v239, v18, v19
	s_nop 1
	v_permlane16_swap_b32_e32 v236, v238
	v_permlane16_swap_b32_e32 v237, v239
	v_lshl_add_u64 v[242:243], v[34:35], 0, v[240:241]
	global_store_dwordx4 v[242:243], v[236:239], off offset:256 sc0 sc1
	s_waitcnt lgkmcnt(0)
	v_add_f32_e32 v16, v16, v17
	ds_bpermute_b32 v17, v153, v16
	s_and_saveexec_b64 s[36:37], s[4:5]
	s_cbranch_execz .LBB0_1620
	s_waitcnt lgkmcnt(0)
	v_add_f32_e32 v18, v16, v17
	v_lshlrev_b64 v[16:17], 6, v[32:33]
	v_lshl_add_u64 v[16:17], s[60:61], 0, v[16:17]
	v_lshl_add_u64 v[16:17], s[30:31], 2, v[16:17]
	s_lshl_b32 s8, s50, 2
	v_lshl_add_u64 v[16:17], v[16:17], 0, s[8:9]
	global_store_dword v[16:17], v18, off
.LBB0_1620:
	s_or_b64 exec, exec, s[36:37]
	v_add_u32_e32 v16, 0xb0, v144
	s_waitcnt lgkmcnt(0)
	v_ashrrev_i32_e32 v17, 31, v16
	v_lshlrev_b64 v[18:19], 11, v[16:17]
	v_lshl_add_u64 v[18:19], s[62:63], 0, v[18:19]
	v_lshl_add_u64 v[18:19], v[142:143], 1, v[18:19]
	v_mov_b64_e32 v[20:21], v[222:223]
	v_lshlrev_b32_e32 v22, 16, v20
	v_and_b32_e32 v23, 0xffff0000, v20
	v_lshlrev_b32_e32 v20, 16, v21
	v_and_b32_e32 v21, 0xffff0000, v21
	v_pk_add_f32 v[14:15], v[14:15], v[20:21]
	v_pk_add_f32 v[12:13], v[12:13], v[22:23]
	s_nop 0
	v_cvt_pk_bf16_f32 v232, v12, v13
	v_cvt_pk_bf16_f32 v233, v14, v15
	v_mul_f32_e32 v13, v13, v13
	s_nop 0
	v_mul_f32_e32 v15, v15, v15
	v_fmac_f32_e32 v13, v12, v12
	v_fmac_f32_e32 v15, v14, v14
	v_add_f32_e32 v12, v13, v15
	v_mov_b64_e32 v[22:23], v[224:225]
	v_lshlrev_b32_e32 v20, 16, v22
	v_and_b32_e32 v21, 0xffff0000, v22
	v_lshlrev_b32_e32 v22, 16, v23
	v_and_b32_e32 v23, 0xffff0000, v23
	v_pk_add_f32 v[10:11], v[10:11], v[22:23]
	v_pk_add_f32 v[8:9], v[8:9], v[20:21]
	s_nop 0
	v_cvt_pk_bf16_f32 v234, v8, v9
	v_cvt_pk_bf16_f32 v235, v10, v11
	v_mul_f32_e32 v9, v9, v9
	s_nop 1
	v_permlane16_swap_b32_e32 v232, v234
	v_permlane16_swap_b32_e32 v233, v235
	v_lshl_add_u64 v[242:243], v[18:19], 0, v[240:241]
	global_store_dwordx4 v[242:243], v[232:235], off sc0 sc1
	v_mul_f32_e32 v11, v11, v11
	v_fmac_f32_e32 v9, v8, v8
	v_fmac_f32_e32 v11, v10, v10
	v_add_f32_e32 v8, v9, v11
	v_add_f32_e32 v8, v12, v8
	v_mov_b64_e32 v[22:23], v[226:227]
	v_lshlrev_b32_e32 v20, 16, v22
	v_and_b32_e32 v21, 0xffff0000, v22
	v_lshlrev_b32_e32 v22, 16, v23
	v_and_b32_e32 v23, 0xffff0000, v23
	v_pk_add_f32 v[6:7], v[6:7], v[22:23]
	v_pk_add_f32 v[4:5], v[4:5], v[20:21]
	s_nop 0
	v_cvt_pk_bf16_f32 v236, v4, v5
	v_cvt_pk_bf16_f32 v237, v6, v7
	v_mul_f32_e32 v5, v5, v5
	v_mul_f32_e32 v7, v7, v7
	v_fmac_f32_e32 v5, v4, v4
	v_fmac_f32_e32 v7, v6, v6
	v_add_f32_e32 v4, v5, v7
	v_add_f32_e32 v8, v8, v4
	s_nop 0
	v_mov_b64_e32 v[22:23], v[228:229]
	v_lshlrev_b32_e32 v4, 16, v22
	v_and_b32_e32 v5, 0xffff0000, v22
	v_lshlrev_b32_e32 v6, 16, v23
	v_and_b32_e32 v7, 0xffff0000, v23
	v_pk_add_f32 v[2:3], v[2:3], v[6:7]
	v_pk_add_f32 v[4:5], v[0:1], v[4:5]
	v_mul_f32_e32 v1, v3, v3
	v_mul_f32_e32 v0, v5, v5
	v_fmac_f32_e32 v0, v4, v4
	v_fmac_f32_e32 v1, v2, v2
	v_add_f32_e32 v0, v0, v1
	v_add_f32_e32 v0, v8, v0
	ds_bpermute_b32 v1, v149, v0
	v_cvt_pk_bf16_f32 v238, v4, v5
	v_cvt_pk_bf16_f32 v239, v2, v3
	s_nop 1
	v_permlane16_swap_b32_e32 v236, v238
	v_permlane16_swap_b32_e32 v237, v239
	v_lshl_add_u64 v[242:243], v[18:19], 0, v[240:241]
	global_store_dwordx4 v[242:243], v[236:239], off offset:256 sc0 sc1
	s_waitcnt lgkmcnt(0)
	v_add_f32_e32 v0, v0, v1
	ds_bpermute_b32 v1, v153, v0
	s_and_saveexec_b64 s[36:37], s[4:5]
	s_cbranch_execz .LBB0_1622
	s_waitcnt lgkmcnt(0)
	v_add_f32_e32 v2, v0, v1
	v_lshlrev_b64 v[0:1], 6, v[16:17]
	v_lshl_add_u64 v[0:1], s[60:61], 0, v[0:1]
	v_lshl_add_u64 v[0:1], s[30:31], 2, v[0:1]
	s_lshl_b32 s8, s50, 2
	v_lshl_add_u64 v[0:1], v[0:1], 0, s[8:9]
	global_store_dword v[0:1], v2, off

.LBB0_1827:
	v_lshl_add_u32 v144, s51, 8, v133
	s_lshl_b32 s22, s10, 8
	v_ashrrev_i32_e32 v145, 31, v144
	s_ashr_i32 s23, s22, 31
	v_lshlrev_b64 v[154:155], 11, v[144:145]
	v_mov_b32_e32 v143, s23
	v_or_b32_e32 v142, s22, v132
	v_lshl_add_u64 v[154:155], s[62:63], 0, v[154:155]
	v_lshl_add_u64 v[154:155], v[142:143], 1, v[154:155]
	global_load_dwordx2 v[164:165], v[154:155], off
	global_load_dwordx2 v[166:167], v[154:155], off offset:32
	global_load_dwordx2 v[168:169], v[154:155], off offset:256
	global_load_dwordx2 v[170:171], v[154:155], off offset:288
	v_add_co_u32_e32 v230, vcc, 0x8000, v154
	s_nop 1
	v_addc_co_u32_e32 v231, vcc, 0, v155, vcc
	global_load_dwordx2 v[172:173], v[230:231], off
	global_load_dwordx2 v[174:175], v[230:231], off offset:32
	global_load_dwordx2 v[176:177], v[230:231], off offset:256
	global_load_dwordx2 v[178:179], v[230:231], off offset:288
	v_add_co_u32_e32 v230, vcc, 0x10000, v154
	s_nop 1
	v_addc_co_u32_e32 v231, vcc, 0, v155, vcc
	global_load_dwordx2 v[180:181], v[230:231], off
	global_load_dwordx2 v[182:183], v[230:231], off offset:32
	global_load_dwordx2 v[184:185], v[230:231], off offset:256
	global_load_dwordx2 v[188:189], v[230:231], off offset:288
	v_add_co_u32_e32 v230, vcc, 0x18000, v154
	s_nop 1
	v_addc_co_u32_e32 v231, vcc, 0, v155, vcc
	global_load_dwordx2 v[190:191], v[230:231], off
	global_load_dwordx2 v[192:193], v[230:231], off offset:32
	global_load_dwordx2 v[194:195], v[230:231], off offset:256
	global_load_dwordx2 v[196:197], v[230:231], off offset:288
	v_add_co_u32_e32 v230, vcc, 0x40000, v154
	s_nop 1
	v_addc_co_u32_e32 v231, vcc, 0, v155, vcc
	global_load_dwordx2 v[198:199], v[230:231], off
	global_load_dwordx2 v[200:201], v[230:231], off offset:32
	global_load_dwordx2 v[202:203], v[230:231], off offset:256
	global_load_dwordx2 v[204:205], v[230:231], off offset:288
	v_add_co_u32_e32 v230, vcc, 0x48000, v154
	s_nop 1
	v_addc_co_u32_e32 v231, vcc, 0, v155, vcc
	global_load_dwordx2 v[206:207], v[230:231], off
	global_load_dwordx2 v[208:209], v[230:231], off offset:32
	global_load_dwordx2 v[210:211], v[230:231], off offset:256
	global_load_dwordx2 v[212:213], v[230:231], off offset:288
	v_add_co_u32_e32 v230, vcc, 0x50000, v154
	s_nop 1
	v_addc_co_u32_e32 v231, vcc, 0, v155, vcc
	global_load_dwordx2 v[214:215], v[230:231], off
	global_load_dwordx2 v[216:217], v[230:231], off offset:32
	global_load_dwordx2 v[218:219], v[230:231], off offset:256
	global_load_dwordx2 v[220:221], v[230:231], off offset:288
	v_add_co_u32_e32 v230, vcc, 0x58000, v154
	s_nop 1
	v_addc_co_u32_e32 v231, vcc, 0, v155, vcc
	global_load_dwordx2 v[222:223], v[230:231], off
	global_load_dwordx2 v[224:225], v[230:231], off offset:32
	global_load_dwordx2 v[226:227], v[230:231], off offset:256
	global_load_dwordx2 v[228:229], v[230:231], off offset:288
	s_waitcnt vmcnt(0)
	v_mbcnt_lo_u32_b32 v240, -1, 0
	v_mbcnt_hi_u32_b32 v240, -1, v240
	v_and_b32_e32 v240, 16, v240
	v_lshrrev_b32_e32 v241, 1, v240
	v_add_u32_e32 v240, v240, v241
	v_mov_b32_e32 v241, 0
	s_lshl_b32 s22, s10, 2
	s_ashr_i32 s23, s22, 31
	v_mov_b64_e32 v[156:157], v[164:165]
	v_lshlrev_b32_e32 v158, 16, v156
	v_and_b32_e32 v159, 0xffff0000, v156
	v_lshlrev_b32_e32 v156, 16, v157
	v_and_b32_e32 v157, 0xffff0000, v157
	v_pk_add_f32 v[126:127], v[126:127], v[156:157]
	v_pk_add_f32 v[124:125], v[124:125], v[158:159]
	s_nop 0
	v_cvt_pk_bf16_f32 v232, v124, v125
	v_cvt_pk_bf16_f32 v233, v126, v127
	v_mul_f32_e32 v125, v125, v125
	s_nop 0
	v_mul_f32_e32 v127, v127, v127
	v_fmac_f32_e32 v125, v124, v124
	v_fmac_f32_e32 v127, v126, v126
	v_add_f32_e32 v124, v125, v127
	v_mov_b64_e32 v[158:159], v[166:167]
	v_lshlrev_b32_e32 v156, 16, v158
	v_and_b32_e32 v157, 0xffff0000, v158
	v_lshlrev_b32_e32 v158, 16, v159
	v_and_b32_e32 v159, 0xffff0000, v159
	v_pk_add_f32 v[122:123], v[122:123], v[158:159]
	v_pk_add_f32 v[120:121], v[120:121], v[156:157]
	s_nop 0
	v_cvt_pk_bf16_f32 v234, v120, v121
	v_cvt_pk_bf16_f32 v235, v122, v123
	v_mul_f32_e32 v121, v121, v121
	s_nop 1
	v_permlane16_swap_b32_e32 v232, v234
	v_permlane16_swap_b32_e32 v233, v235
	v_lshl_add_u64 v[242:243], v[154:155], 0, v[240:241]
	global_store_dwordx4 v[242:243], v[232:235], off sc0 sc1
	v_mul_f32_e32 v123, v123, v123
	v_fmac_f32_e32 v121, v120, v120
	v_fmac_f32_e32 v123, v122, v122
	v_add_f32_e32 v120, v121, v123
	v_add_f32_e32 v120, v124, v120
	v_mov_b64_e32 v[158:159], v[168:169]
	v_lshlrev_b32_e32 v156, 16, v158
	v_and_b32_e32 v157, 0xffff0000, v158
	v_lshlrev_b32_e32 v158, 16, v159
	v_and_b32_e32 v159, 0xffff0000, v159
	v_pk_add_f32 v[118:119], v[118:119], v[158:159]
	v_pk_add_f32 v[116:117], v[116:117], v[156:157]
	s_nop 0
	v_cvt_pk_bf16_f32 v236, v116, v117
	v_cvt_pk_bf16_f32 v237, v118, v119
	v_mul_f32_e32 v117, v117, v117
	v_mul_f32_e32 v119, v119, v119
	v_fmac_f32_e32 v117, v116, v116
	v_fmac_f32_e32 v119, v118, v118
	v_add_f32_e32 v116, v117, v119
	v_add_f32_e32 v120, v120, v116
	s_nop 0
	v_mov_b64_e32 v[158:159], v[170:171]
	v_lshlrev_b32_e32 v116, 16, v158
	v_and_b32_e32 v117, 0xffff0000, v158
	v_lshlrev_b32_e32 v118, 16, v159
	v_and_b32_e32 v119, 0xffff0000, v159
	v_pk_add_f32 v[114:115], v[114:115], v[118:119]
	v_pk_add_f32 v[116:117], v[112:113], v[116:117]
	v_mul_f32_e32 v113, v115, v115
	v_mul_f32_e32 v112, v117, v117
	v_fmac_f32_e32 v112, v116, v116
	v_fmac_f32_e32 v113, v114, v114
	v_add_f32_e32 v112, v112, v113
	v_add_f32_e32 v112, v120, v112
	ds_bpermute_b32 v113, v149, v112
	v_cvt_pk_bf16_f32 v238, v116, v117
	v_cvt_pk_bf16_f32 v239, v114, v115
	s_nop 1
	v_permlane16_swap_b32_e32 v236, v238
	v_permlane16_swap_b32_e32 v237, v239
	v_lshl_add_u64 v[242:243], v[154:155], 0, v[240:241]
	global_store_dwordx4 v[242:243], v[236:239], off offset:256 sc0 sc1
	s_waitcnt lgkmcnt(0)
	v_add_f32_e32 v112, v112, v113
	ds_bpermute_b32 v113, v153, v112
	s_and_saveexec_b64 s[24:25], s[8:9]
	s_cbranch_execz .LBB0_1829
	s_waitcnt lgkmcnt(0)
	v_add_f32_e32 v114, v112, v113
	v_lshlrev_b64 v[112:113], 6, v[144:145]
	v_lshl_add_u64 v[112:113], s[60:61], 0, v[112:113]
	v_lshl_add_u64 v[112:113], s[22:23], 2, v[112:113]
	s_lshl_b32 s10, s40, 2
	v_lshl_add_u64 v[112:113], v[112:113], 0, s[10:11]
	global_store_dword v[112:113], v114, off
.LBB0_1829:
	s_or_b64 exec, exec, s[24:25]
	v_or_b32_e32 v112, 16, v144
	s_waitcnt lgkmcnt(0)
	v_ashrrev_i32_e32 v113, 31, v112
	v_lshlrev_b64 v[114:115], 11, v[112:113]
	v_lshl_add_u64 v[114:115], s[62:63], 0, v[114:115]
	v_lshl_add_u64 v[114:115], v[142:143], 1, v[114:115]
	v_mov_b64_e32 v[116:117], v[172:173]
	v_lshlrev_b32_e32 v118, 16, v116
	v_and_b32_e32 v119, 0xffff0000, v116
	v_lshlrev_b32_e32 v116, 16, v117
	v_and_b32_e32 v117, 0xffff0000, v117
	v_pk_add_f32 v[110:111], v[110:111], v[116:117]
	v_pk_add_f32 v[108:109], v[108:109], v[118:119]
	s_nop 0
	v_cvt_pk_bf16_f32 v232, v108, v109
	v_cvt_pk_bf16_f32 v233, v110, v111
	v_mul_f32_e32 v109, v109, v109
	s_nop 0
	v_mul_f32_e32 v111, v111, v111
	v_fmac_f32_e32 v109, v108, v108
	v_fmac_f32_e32 v111, v110, v110
	v_add_f32_e32 v108, v109, v111
	v_mov_b64_e32 v[118:119], v[174:175]
	v_lshlrev_b32_e32 v116, 16, v118
	v_and_b32_e32 v117, 0xffff0000, v118
	v_lshlrev_b32_e32 v118, 16, v119
	v_and_b32_e32 v119, 0xffff0000, v119
	v_pk_add_f32 v[106:107], v[106:107], v[118:119]
	v_pk_add_f32 v[104:105], v[104:105], v[116:117]
	s_nop 0
	v_cvt_pk_bf16_f32 v234, v104, v105
	v_cvt_pk_bf16_f32 v235, v106, v107
	v_mul_f32_e32 v105, v105, v105
	s_nop 1
	v_permlane16_swap_b32_e32 v232, v234
	v_permlane16_swap_b32_e32 v233, v235
	v_lshl_add_u64 v[242:243], v[114:115], 0, v[240:241]
	global_store_dwordx4 v[242:243], v[232:235], off sc0 sc1
	v_mul_f32_e32 v107, v107, v107
	v_fmac_f32_e32 v105, v104, v104
	v_fmac_f32_e32 v107, v106, v106
	v_add_f32_e32 v104, v105, v107
	v_add_f32_e32 v104, v108, v104
	v_mov_b64_e32 v[118:119], v[176:177]
	v_lshlrev_b32_e32 v116, 16, v118
	v_and_b32_e32 v117, 0xffff0000, v118
	v_lshlrev_b32_e32 v118, 16, v119
	v_and_b32_e32 v119, 0xffff0000, v119
	v_pk_add_f32 v[102:103], v[102:103], v[118:119]
	v_pk_add_f32 v[100:101], v[100:101], v[116:117]
	s_nop 0
	v_cvt_pk_bf16_f32 v236, v100, v101
	v_cvt_pk_bf16_f32 v237, v102, v103
	v_mul_f32_e32 v101, v101, v101
	v_mul_f32_e32 v103, v103, v103
	v_fmac_f32_e32 v101, v100, v100
	v_fmac_f32_e32 v103, v102, v102
	v_add_f32_e32 v100, v101, v103
	v_add_f32_e32 v104, v104, v100
	s_nop 0
	v_mov_b64_e32 v[118:119], v[178:179]
	v_lshlrev_b32_e32 v100, 16, v118
	v_and_b32_e32 v101, 0xffff0000, v118
	v_lshlrev_b32_e32 v102, 16, v119
	v_and_b32_e32 v103, 0xffff0000, v119
	v_pk_add_f32 v[98:99], v[98:99], v[102:103]
	v_pk_add_f32 v[100:101], v[96:97], v[100:101]
	v_mul_f32_e32 v97, v99, v99
	v_mul_f32_e32 v96, v101, v101
	v_fmac_f32_e32 v96, v100, v100
	v_fmac_f32_e32 v97, v98, v98
	v_add_f32_e32 v96, v96, v97
	v_add_f32_e32 v96, v104, v96
	ds_bpermute_b32 v97, v149, v96
	v_cvt_pk_bf16_f32 v238, v100, v101
	v_cvt_pk_bf16_f32 v239, v98, v99
	s_nop 1
	v_permlane16_swap_b32_e32 v236, v238
	v_permlane16_swap_b32_e32 v237, v239
	v_lshl_add_u64 v[242:243], v[114:115], 0, v[240:241]
	global_store_dwordx4 v[242:243], v[236:239], off offset:256 sc0 sc1
	s_waitcnt lgkmcnt(0)
	v_add_f32_e32 v96, v96, v97
	ds_bpermute_b32 v97, v153, v96
	s_and_saveexec_b64 s[24:25], s[8:9]
	s_cbranch_execz .LBB0_1831
	s_waitcnt lgkmcnt(0)
	v_add_f32_e32 v98, v96, v97
	v_lshlrev_b64 v[96:97], 6, v[112:113]
	v_lshl_add_u64 v[96:97], s[60:61], 0, v[96:97]
	v_lshl_add_u64 v[96:97], s[22:23], 2, v[96:97]
	s_lshl_b32 s10, s40, 2
	v_lshl_add_u64 v[96:97], v[96:97], 0, s[10:11]
	global_store_dword v[96:97], v98, off
.LBB0_1831:
	s_or_b64 exec, exec, s[24:25]
	v_or_b32_e32 v96, 32, v144
	s_waitcnt lgkmcnt(0)
	v_ashrrev_i32_e32 v97, 31, v96
	v_lshlrev_b64 v[98:99], 11, v[96:97]
	v_lshl_add_u64 v[98:99], s[62:63], 0, v[98:99]
	v_lshl_add_u64 v[98:99], v[142:143], 1, v[98:99]
	v_mov_b64_e32 v[100:101], v[180:181]
	v_lshlrev_b32_e32 v102, 16, v100
	v_and_b32_e32 v103, 0xffff0000, v100
	v_lshlrev_b32_e32 v100, 16, v101
	v_and_b32_e32 v101, 0xffff0000, v101
	v_pk_add_f32 v[94:95], v[94:95], v[100:101]
	v_pk_add_f32 v[92:93], v[92:93], v[102:103]
	s_nop 0
	v_cvt_pk_bf16_f32 v232, v92, v93
	v_cvt_pk_bf16_f32 v233, v94, v95
	v_mul_f32_e32 v93, v93, v93
	s_nop 0
	v_mul_f32_e32 v95, v95, v95
	v_fmac_f32_e32 v93, v92, v92
	v_fmac_f32_e32 v95, v94, v94
	v_add_f32_e32 v92, v93, v95
	v_mov_b64_e32 v[102:103], v[182:183]
	v_lshlrev_b32_e32 v100, 16, v102
	v_and_b32_e32 v101, 0xffff0000, v102
	v_lshlrev_b32_e32 v102, 16, v103
	v_and_b32_e32 v103, 0xffff0000, v103
	v_pk_add_f32 v[90:91], v[90:91], v[102:103]
	v_pk_add_f32 v[88:89], v[88:89], v[100:101]
	s_nop 0
	v_cvt_pk_bf16_f32 v234, v88, v89
	v_cvt_pk_bf16_f32 v235, v90, v91
	v_mul_f32_e32 v89, v89, v89
	s_nop 1
	v_permlane16_swap_b32_e32 v232, v234
	v_permlane16_swap_b32_e32 v233, v235
	v_lshl_add_u64 v[242:243], v[98:99], 0, v[240:241]
	global_store_dwordx4 v[242:243], v[232:235], off sc0 sc1
	v_mul_f32_e32 v91, v91, v91
	v_fmac_f32_e32 v89, v88, v88
	v_fmac_f32_e32 v91, v90, v90
	v_add_f32_e32 v88, v89, v91
	v_add_f32_e32 v88, v92, v88
	v_mov_b64_e32 v[102:103], v[184:185]
	v_lshlrev_b32_e32 v100, 16, v102
	v_and_b32_e32 v101, 0xffff0000, v102
	v_lshlrev_b32_e32 v102, 16, v103
	v_and_b32_e32 v103, 0xffff0000, v103
	v_pk_add_f32 v[86:87], v[86:87], v[102:103]
	v_pk_add_f32 v[84:85], v[84:85], v[100:101]
	s_nop 0
	v_cvt_pk_bf16_f32 v236, v84, v85
	v_cvt_pk_bf16_f32 v237, v86, v87
	v_mul_f32_e32 v85, v85, v85
	v_mul_f32_e32 v87, v87, v87
	v_fmac_f32_e32 v85, v84, v84
	v_fmac_f32_e32 v87, v86, v86
	v_add_f32_e32 v84, v85, v87
	v_add_f32_e32 v88, v88, v84
	s_nop 0
	v_mov_b64_e32 v[102:103], v[188:189]
	v_lshlrev_b32_e32 v84, 16, v102
	v_and_b32_e32 v85, 0xffff0000, v102
	v_lshlrev_b32_e32 v86, 16, v103
	v_and_b32_e32 v87, 0xffff0000, v103
	v_pk_add_f32 v[82:83], v[82:83], v[86:87]
	v_pk_add_f32 v[84:85], v[80:81], v[84:85]
	v_mul_f32_e32 v81, v83, v83
	v_mul_f32_e32 v80, v85, v85
	v_fmac_f32_e32 v80, v84, v84
	v_fmac_f32_e32 v81, v82, v82
	v_add_f32_e32 v80, v80, v81
	v_add_f32_e32 v80, v88, v80
	ds_bpermute_b32 v81, v149, v80
	v_cvt_pk_bf16_f32 v238, v84, v85
	v_cvt_pk_bf16_f32 v239, v82, v83
	s_nop 1
	v_permlane16_swap_b32_e32 v236, v238
	v_permlane16_swap_b32_e32 v237, v239
	v_lshl_add_u64 v[242:243], v[98:99], 0, v[240:241]
	global_store_dwordx4 v[242:243], v[236:239], off offset:256 sc0 sc1
	s_waitcnt lgkmcnt(0)
	v_add_f32_e32 v80, v80, v81
	ds_bpermute_b32 v81, v153, v80
	s_and_saveexec_b64 s[24:25], s[8:9]
	s_cbranch_execz .LBB0_1833
	s_waitcnt lgkmcnt(0)
	v_add_f32_e32 v82, v80, v81
	v_lshlrev_b64 v[80:81], 6, v[96:97]
	v_lshl_add_u64 v[80:81], s[60:61], 0, v[80:81]
	v_lshl_add_u64 v[80:81], s[22:23], 2, v[80:81]
	s_lshl_b32 s10, s40, 2
	v_lshl_add_u64 v[80:81], v[80:81], 0, s[10:11]
	global_store_dword v[80:81], v82, off
.LBB0_1833:
	s_or_b64 exec, exec, s[24:25]
	v_or_b32_e32 v80, 48, v144
	s_waitcnt lgkmcnt(0)
	v_ashrrev_i32_e32 v81, 31, v80
	v_lshlrev_b64 v[82:83], 11, v[80:81]
	v_lshl_add_u64 v[82:83], s[62:63], 0, v[82:83]
	v_lshl_add_u64 v[82:83], v[142:143], 1, v[82:83]
	v_mov_b64_e32 v[84:85], v[190:191]
	v_lshlrev_b32_e32 v86, 16, v84
	v_and_b32_e32 v87, 0xffff0000, v84
	v_lshlrev_b32_e32 v84, 16, v85
	v_and_b32_e32 v85, 0xffff0000, v85
	v_pk_add_f32 v[78:79], v[78:79], v[84:85]
	v_pk_add_f32 v[76:77], v[76:77], v[86:87]
	s_nop 0
	v_cvt_pk_bf16_f32 v232, v76, v77
	v_cvt_pk_bf16_f32 v233, v78, v79
	v_mul_f32_e32 v77, v77, v77
	s_nop 0
	v_mul_f32_e32 v79, v79, v79
	v_fmac_f32_e32 v77, v76, v76
	v_fmac_f32_e32 v79, v78, v78
	v_add_f32_e32 v76, v77, v79
	v_mov_b64_e32 v[86:87], v[192:193]
	v_lshlrev_b32_e32 v84, 16, v86
	v_and_b32_e32 v85, 0xffff0000, v86
	v_lshlrev_b32_e32 v86, 16, v87
	v_and_b32_e32 v87, 0xffff0000, v87
	v_pk_add_f32 v[74:75], v[74:75], v[86:87]
	v_pk_add_f32 v[72:73], v[72:73], v[84:85]
	s_nop 0
	v_cvt_pk_bf16_f32 v234, v72, v73
	v_cvt_pk_bf16_f32 v235, v74, v75
	v_mul_f32_e32 v73, v73, v73
	s_nop 1
	v_permlane16_swap_b32_e32 v232, v234
	v_permlane16_swap_b32_e32 v233, v235
	v_lshl_add_u64 v[242:243], v[82:83], 0, v[240:241]
	global_store_dwordx4 v[242:243], v[232:235], off sc0 sc1
	v_mul_f32_e32 v75, v75, v75
	v_fmac_f32_e32 v73, v72, v72
	v_fmac_f32_e32 v75, v74, v74
	v_add_f32_e32 v72, v73, v75
	v_add_f32_e32 v72, v76, v72
	v_mov_b64_e32 v[86:87], v[194:195]
	v_lshlrev_b32_e32 v84, 16, v86
	v_and_b32_e32 v85, 0xffff0000, v86
	v_lshlrev_b32_e32 v86, 16, v87
	v_and_b32_e32 v87, 0xffff0000, v87
	v_pk_add_f32 v[70:71], v[70:71], v[86:87]
	v_pk_add_f32 v[68:69], v[68:69], v[84:85]
	s_nop 0
	v_cvt_pk_bf16_f32 v236, v68, v69
	v_cvt_pk_bf16_f32 v237, v70, v71
	v_mul_f32_e32 v69, v69, v69
	v_mul_f32_e32 v71, v71, v71
	v_fmac_f32_e32 v69, v68, v68
	v_fmac_f32_e32 v71, v70, v70
	v_add_f32_e32 v68, v69, v71
	v_add_f32_e32 v72, v72, v68
	s_nop 0
	v_mov_b64_e32 v[86:87], v[196:197]
	v_lshlrev_b32_e32 v68, 16, v86
	v_and_b32_e32 v69, 0xffff0000, v86
	v_lshlrev_b32_e32 v70, 16, v87
	v_and_b32_e32 v71, 0xffff0000, v87
	v_pk_add_f32 v[66:67], v[66:67], v[70:71]
	v_pk_add_f32 v[68:69], v[64:65], v[68:69]
	v_mul_f32_e32 v65, v67, v67
	v_mul_f32_e32 v64, v69, v69
	v_fmac_f32_e32 v64, v68, v68
	v_fmac_f32_e32 v65, v66, v66
	v_add_f32_e32 v64, v64, v65
	v_add_f32_e32 v64, v72, v64
	ds_bpermute_b32 v65, v149, v64
	v_cvt_pk_bf16_f32 v238, v68, v69
	v_cvt_pk_bf16_f32 v239, v66, v67
	s_nop 1
	v_permlane16_swap_b32_e32 v236, v238
	v_permlane16_swap_b32_e32 v237, v239
	v_lshl_add_u64 v[242:243], v[82:83], 0, v[240:241]
	global_store_dwordx4 v[242:243], v[236:239], off offset:256 sc0 sc1
	s_waitcnt lgkmcnt(0)
	v_add_f32_e32 v64, v64, v65
	ds_bpermute_b32 v65, v153, v64
	s_and_saveexec_b64 s[24:25], s[8:9]
	s_cbranch_execz .LBB0_1835
	s_waitcnt lgkmcnt(0)
	v_add_f32_e32 v66, v64, v65
	v_lshlrev_b64 v[64:65], 6, v[80:81]
	v_lshl_add_u64 v[64:65], s[60:61], 0, v[64:65]
	v_lshl_add_u64 v[64:65], s[22:23], 2, v[64:65]
	s_lshl_b32 s10, s40, 2
	v_lshl_add_u64 v[64:65], v[64:65], 0, s[10:11]
	global_store_dword v[64:65], v66, off
.LBB0_1835:
	s_or_b64 exec, exec, s[24:25]
	v_add_u32_e32 v64, 0x80, v144
	s_waitcnt lgkmcnt(0)
	v_ashrrev_i32_e32 v65, 31, v64
	v_lshlrev_b64 v[66:67], 11, v[64:65]
	v_lshl_add_u64 v[66:67], s[62:63], 0, v[66:67]
	v_lshl_add_u64 v[66:67], v[142:143], 1, v[66:67]
	v_mov_b64_e32 v[68:69], v[198:199]
	v_lshlrev_b32_e32 v70, 16, v68
	v_and_b32_e32 v71, 0xffff0000, v68
	v_lshlrev_b32_e32 v68, 16, v69
	v_and_b32_e32 v69, 0xffff0000, v69
	v_pk_add_f32 v[62:63], v[62:63], v[68:69]
	v_pk_add_f32 v[60:61], v[60:61], v[70:71]
	s_nop 0
	v_cvt_pk_bf16_f32 v232, v60, v61
	v_cvt_pk_bf16_f32 v233, v62, v63
	v_mul_f32_e32 v61, v61, v61
	s_nop 0
	v_mul_f32_e32 v63, v63, v63
	v_fmac_f32_e32 v61, v60, v60
	v_fmac_f32_e32 v63, v62, v62
	v_add_f32_e32 v60, v61, v63
	v_mov_b64_e32 v[70:71], v[200:201]
	v_lshlrev_b32_e32 v68, 16, v70
	v_and_b32_e32 v69, 0xffff0000, v70
	v_lshlrev_b32_e32 v70, 16, v71
	v_and_b32_e32 v71, 0xffff0000, v71
	v_pk_add_f32 v[58:59], v[58:59], v[70:71]
	v_pk_add_f32 v[56:57], v[56:57], v[68:69]
	s_nop 0
	v_cvt_pk_bf16_f32 v234, v56, v57
	v_cvt_pk_bf16_f32 v235, v58, v59
	v_mul_f32_e32 v57, v57, v57
	s_nop 1
	v_permlane16_swap_b32_e32 v232, v234
	v_permlane16_swap_b32_e32 v233, v235
	v_lshl_add_u64 v[242:243], v[66:67], 0, v[240:241]
	global_store_dwordx4 v[242:243], v[232:235], off sc0 sc1
	v_mul_f32_e32 v59, v59, v59
	v_fmac_f32_e32 v57, v56, v56
	v_fmac_f32_e32 v59, v58, v58
	v_add_f32_e32 v56, v57, v59
	v_add_f32_e32 v56, v60, v56
	v_mov_b64_e32 v[70:71], v[202:203]
	v_lshlrev_b32_e32 v68, 16, v70
	v_and_b32_e32 v69, 0xffff0000, v70
	v_lshlrev_b32_e32 v70, 16, v71
	v_and_b32_e32 v71, 0xffff0000, v71
	v_pk_add_f32 v[54:55], v[54:55], v[70:71]
	v_pk_add_f32 v[52:53], v[52:53], v[68:69]
	s_nop 0
	v_cvt_pk_bf16_f32 v236, v52, v53
	v_cvt_pk_bf16_f32 v237, v54, v55
	v_mul_f32_e32 v53, v53, v53
	v_mul_f32_e32 v55, v55, v55
	v_fmac_f32_e32 v53, v52, v52
	v_fmac_f32_e32 v55, v54, v54
	v_add_f32_e32 v52, v53, v55
	v_add_f32_e32 v56, v56, v52
	s_nop 0
	v_mov_b64_e32 v[70:71], v[204:205]
	v_lshlrev_b32_e32 v52, 16, v70
	v_and_b32_e32 v53, 0xffff0000, v70
	v_lshlrev_b32_e32 v54, 16, v71
	v_and_b32_e32 v55, 0xffff0000, v71
	v_pk_add_f32 v[50:51], v[50:51], v[54:55]
	v_pk_add_f32 v[52:53], v[48:49], v[52:53]
	v_mul_f32_e32 v49, v51, v51
	v_mul_f32_e32 v48, v53, v53
	v_fmac_f32_e32 v48, v52, v52
	v_fmac_f32_e32 v49, v50, v50
	v_add_f32_e32 v48, v48, v49
	v_add_f32_e32 v48, v56, v48
	ds_bpermute_b32 v49, v149, v48
	v_cvt_pk_bf16_f32 v238, v52, v53
	v_cvt_pk_bf16_f32 v239, v50, v51
	s_nop 1
	v_permlane16_swap_b32_e32 v236, v238
	v_permlane16_swap_b32_e32 v237, v239
	v_lshl_add_u64 v[242:243], v[66:67], 0, v[240:241]
	global_store_dwordx4 v[242:243], v[236:239], off offset:256 sc0 sc1
	s_waitcnt lgkmcnt(0)
	v_add_f32_e32 v48, v48, v49
	ds_bpermute_b32 v49, v153, v48
	s_and_saveexec_b64 s[24:25], s[8:9]
	s_cbranch_execz .LBB0_1837
	s_waitcnt lgkmcnt(0)
	v_add_f32_e32 v50, v48, v49
	v_lshlrev_b64 v[48:49], 6, v[64:65]
	v_lshl_add_u64 v[48:49], s[60:61], 0, v[48:49]
	v_lshl_add_u64 v[48:49], s[22:23], 2, v[48:49]
	s_lshl_b32 s10, s40, 2
	v_lshl_add_u64 v[48:49], v[48:49], 0, s[10:11]
	global_store_dword v[48:49], v50, off
.LBB0_1837:
	s_or_b64 exec, exec, s[24:25]
	v_add_u32_e32 v48, 0x90, v144
	s_waitcnt lgkmcnt(0)
	v_ashrrev_i32_e32 v49, 31, v48
	v_lshlrev_b64 v[50:51], 11, v[48:49]
	v_lshl_add_u64 v[50:51], s[62:63], 0, v[50:51]
	v_lshl_add_u64 v[50:51], v[142:143], 1, v[50:51]
	v_mov_b64_e32 v[52:53], v[206:207]
	v_lshlrev_b32_e32 v54, 16, v52
	v_and_b32_e32 v55, 0xffff0000, v52
	v_lshlrev_b32_e32 v52, 16, v53
	v_and_b32_e32 v53, 0xffff0000, v53
	v_pk_add_f32 v[46:47], v[46:47], v[52:53]
	v_pk_add_f32 v[44:45], v[44:45], v[54:55]
	s_nop 0
	v_cvt_pk_bf16_f32 v232, v44, v45
	v_cvt_pk_bf16_f32 v233, v46, v47
	v_mul_f32_e32 v45, v45, v45
	s_nop 0
	v_mul_f32_e32 v47, v47, v47
	v_fmac_f32_e32 v45, v44, v44
	v_fmac_f32_e32 v47, v46, v46
	v_add_f32_e32 v44, v45, v47
	v_mov_b64_e32 v[54:55], v[208:209]
	v_lshlrev_b32_e32 v52, 16, v54
	v_and_b32_e32 v53, 0xffff0000, v54
	v_lshlrev_b32_e32 v54, 16, v55
	v_and_b32_e32 v55, 0xffff0000, v55
	v_pk_add_f32 v[42:43], v[42:43], v[54:55]
	v_pk_add_f32 v[40:41], v[40:41], v[52:53]
	s_nop 0
	v_cvt_pk_bf16_f32 v234, v40, v41
	v_cvt_pk_bf16_f32 v235, v42, v43
	v_mul_f32_e32 v41, v41, v41
	s_nop 1
	v_permlane16_swap_b32_e32 v232, v234
	v_permlane16_swap_b32_e32 v233, v235
	v_lshl_add_u64 v[242:243], v[50:51], 0, v[240:241]
	global_store_dwordx4 v[242:243], v[232:235], off sc0 sc1
	v_mul_f32_e32 v43, v43, v43
	v_fmac_f32_e32 v41, v40, v40
	v_fmac_f32_e32 v43, v42, v42
	v_add_f32_e32 v40, v41, v43
	v_add_f32_e32 v40, v44, v40
	v_mov_b64_e32 v[54:55], v[210:211]
	v_lshlrev_b32_e32 v52, 16, v54
	v_and_b32_e32 v53, 0xffff0000, v54
	v_lshlrev_b32_e32 v54, 16, v55
	v_and_b32_e32 v55, 0xffff0000, v55
	v_pk_add_f32 v[38:39], v[38:39], v[54:55]
	v_pk_add_f32 v[36:37], v[36:37], v[52:53]
	s_nop 0
	v_cvt_pk_bf16_f32 v236, v36, v37
	v_cvt_pk_bf16_f32 v237, v38, v39
	v_mul_f32_e32 v37, v37, v37
	v_mul_f32_e32 v39, v39, v39
	v_fmac_f32_e32 v37, v36, v36
	v_fmac_f32_e32 v39, v38, v38
	v_add_f32_e32 v36, v37, v39
	v_add_f32_e32 v40, v40, v36
	s_nop 0
	v_mov_b64_e32 v[54:55], v[212:213]
	v_lshlrev_b32_e32 v36, 16, v54
	v_and_b32_e32 v37, 0xffff0000, v54
	v_lshlrev_b32_e32 v38, 16, v55
	v_and_b32_e32 v39, 0xffff0000, v55
	v_pk_add_f32 v[34:35], v[34:35], v[38:39]
	v_pk_add_f32 v[36:37], v[32:33], v[36:37]
	v_mul_f32_e32 v33, v35, v35
	v_mul_f32_e32 v32, v37, v37
	v_fmac_f32_e32 v32, v36, v36
	v_fmac_f32_e32 v33, v34, v34
	v_add_f32_e32 v32, v32, v33
	v_add_f32_e32 v32, v40, v32
	ds_bpermute_b32 v33, v149, v32
	v_cvt_pk_bf16_f32 v238, v36, v37
	v_cvt_pk_bf16_f32 v239, v34, v35
	s_nop 1
	v_permlane16_swap_b32_e32 v236, v238
	v_permlane16_swap_b32_e32 v237, v239
	v_lshl_add_u64 v[242:243], v[50:51], 0, v[240:241]
	global_store_dwordx4 v[242:243], v[236:239], off offset:256 sc0 sc1
	s_waitcnt lgkmcnt(0)
	v_add_f32_e32 v32, v32, v33
	ds_bpermute_b32 v33, v153, v32
	s_and_saveexec_b64 s[24:25], s[8:9]
	s_cbranch_execz .LBB0_1839
	s_waitcnt lgkmcnt(0)
	v_add_f32_e32 v34, v32, v33
	v_lshlrev_b64 v[32:33], 6, v[48:49]
	v_lshl_add_u64 v[32:33], s[60:61], 0, v[32:33]
	v_lshl_add_u64 v[32:33], s[22:23], 2, v[32:33]
	s_lshl_b32 s10, s40, 2
	v_lshl_add_u64 v[32:33], v[32:33], 0, s[10:11]
	global_store_dword v[32:33], v34, off
.LBB0_1839:
	s_or_b64 exec, exec, s[24:25]
	v_add_u32_e32 v32, 0xa0, v144
	s_waitcnt lgkmcnt(0)
	v_ashrrev_i32_e32 v33, 31, v32
	v_lshlrev_b64 v[34:35], 11, v[32:33]
	v_lshl_add_u64 v[34:35], s[62:63], 0, v[34:35]
	v_lshl_add_u64 v[34:35], v[142:143], 1, v[34:35]
	v_mov_b64_e32 v[36:37], v[214:215]
	v_lshlrev_b32_e32 v38, 16, v36
	v_and_b32_e32 v39, 0xffff0000, v36
	v_lshlrev_b32_e32 v36, 16, v37
	v_and_b32_e32 v37, 0xffff0000, v37
	v_pk_add_f32 v[30:31], v[30:31], v[36:37]
	v_pk_add_f32 v[28:29], v[28:29], v[38:39]
	s_nop 0
	v_cvt_pk_bf16_f32 v232, v28, v29
	v_cvt_pk_bf16_f32 v233, v30, v31
	v_mul_f32_e32 v29, v29, v29
	s_nop 0
	v_mul_f32_e32 v31, v31, v31
	v_fmac_f32_e32 v29, v28, v28
	v_fmac_f32_e32 v31, v30, v30
	v_add_f32_e32 v28, v29, v31
	v_mov_b64_e32 v[38:39], v[216:217]
	v_lshlrev_b32_e32 v36, 16, v38
	v_and_b32_e32 v37, 0xffff0000, v38
	v_lshlrev_b32_e32 v38, 16, v39
	v_and_b32_e32 v39, 0xffff0000, v39
	v_pk_add_f32 v[26:27], v[26:27], v[38:39]
	v_pk_add_f32 v[24:25], v[24:25], v[36:37]
	s_nop 0
	v_cvt_pk_bf16_f32 v234, v24, v25
	v_cvt_pk_bf16_f32 v235, v26, v27
	v_mul_f32_e32 v25, v25, v25
	s_nop 1
	v_permlane16_swap_b32_e32 v232, v234
	v_permlane16_swap_b32_e32 v233, v235
	v_lshl_add_u64 v[242:243], v[34:35], 0, v[240:241]
	global_store_dwordx4 v[242:243], v[232:235], off sc0 sc1
	v_mul_f32_e32 v27, v27, v27
	v_fmac_f32_e32 v25, v24, v24
	v_fmac_f32_e32 v27, v26, v26
	v_add_f32_e32 v24, v25, v27
	v_add_f32_e32 v24, v28, v24
	v_mov_b64_e32 v[38:39], v[218:219]
	v_lshlrev_b32_e32 v36, 16, v38
	v_and_b32_e32 v37, 0xffff0000, v38
	v_lshlrev_b32_e32 v38, 16, v39
	v_and_b32_e32 v39, 0xffff0000, v39
	v_pk_add_f32 v[22:23], v[22:23], v[38:39]
	v_pk_add_f32 v[20:21], v[20:21], v[36:37]
	s_nop 0
	v_cvt_pk_bf16_f32 v236, v20, v21
	v_cvt_pk_bf16_f32 v237, v22, v23
	v_mul_f32_e32 v21, v21, v21
	v_mul_f32_e32 v23, v23, v23
	v_fmac_f32_e32 v21, v20, v20
	v_fmac_f32_e32 v23, v22, v22
	v_add_f32_e32 v20, v21, v23
	v_add_f32_e32 v24, v24, v20
	s_nop 0
	v_mov_b64_e32 v[38:39], v[220:221]
	v_lshlrev_b32_e32 v20, 16, v38
	v_and_b32_e32 v21, 0xffff0000, v38
	v_lshlrev_b32_e32 v22, 16, v39
	v_and_b32_e32 v23, 0xffff0000, v39
	v_pk_add_f32 v[18:19], v[18:19], v[22:23]
	v_pk_add_f32 v[20:21], v[16:17], v[20:21]
	v_mul_f32_e32 v17, v19, v19
	v_mul_f32_e32 v16, v21, v21
	v_fmac_f32_e32 v16, v20, v20
	v_fmac_f32_e32 v17, v18, v18
	v_add_f32_e32 v16, v16, v17
	v_add_f32_e32 v16, v24, v16
	ds_bpermute_b32 v17, v149, v16
	v_cvt_pk_bf16_f32 v238, v20, v21
	v_cvt_pk_bf16_f32 v239, v18, v19
	s_nop 1
	v_permlane16_swap_b32_e32 v236, v238
	v_permlane16_swap_b32_e32 v237, v239
	v_lshl_add_u64 v[242:243], v[34:35], 0, v[240:241]
	global_store_dwordx4 v[242:243], v[236:239], off offset:256 sc0 sc1
	s_waitcnt lgkmcnt(0)
	v_add_f32_e32 v16, v16, v17
	ds_bpermute_b32 v17, v153, v16
	s_and_saveexec_b64 s[24:25], s[8:9]
	s_cbranch_execz .LBB0_1841
	s_waitcnt lgkmcnt(0)
	v_add_f32_e32 v18, v16, v17
	v_lshlrev_b64 v[16:17], 6, v[32:33]
	v_lshl_add_u64 v[16:17], s[60:61], 0, v[16:17]
	v_lshl_add_u64 v[16:17], s[22:23], 2, v[16:17]
	s_lshl_b32 s10, s40, 2
	v_lshl_add_u64 v[16:17], v[16:17], 0, s[10:11]
	global_store_dword v[16:17], v18, off
.LBB0_1841:
	s_or_b64 exec, exec, s[24:25]
	v_add_u32_e32 v16, 0xb0, v144
	s_waitcnt lgkmcnt(0)
	v_ashrrev_i32_e32 v17, 31, v16
	v_lshlrev_b64 v[18:19], 11, v[16:17]
	v_lshl_add_u64 v[18:19], s[62:63], 0, v[18:19]
	v_lshl_add_u64 v[18:19], v[142:143], 1, v[18:19]
	v_mov_b64_e32 v[20:21], v[222:223]
	v_lshlrev_b32_e32 v22, 16, v20
	v_and_b32_e32 v23, 0xffff0000, v20
	v_lshlrev_b32_e32 v20, 16, v21
	v_and_b32_e32 v21, 0xffff0000, v21
	v_pk_add_f32 v[14:15], v[14:15], v[20:21]
	v_pk_add_f32 v[12:13], v[12:13], v[22:23]
	s_nop 0
	v_cvt_pk_bf16_f32 v232, v12, v13
	v_cvt_pk_bf16_f32 v233, v14, v15
	v_mul_f32_e32 v13, v13, v13
	s_nop 0
	v_mul_f32_e32 v15, v15, v15
	v_fmac_f32_e32 v13, v12, v12
	v_fmac_f32_e32 v15, v14, v14
	v_add_f32_e32 v12, v13, v15
	v_mov_b64_e32 v[22:23], v[224:225]
	v_lshlrev_b32_e32 v20, 16, v22
	v_and_b32_e32 v21, 0xffff0000, v22
	v_lshlrev_b32_e32 v22, 16, v23
	v_and_b32_e32 v23, 0xffff0000, v23
	v_pk_add_f32 v[10:11], v[10:11], v[22:23]
	v_pk_add_f32 v[8:9], v[8:9], v[20:21]
	s_nop 0
	v_cvt_pk_bf16_f32 v234, v8, v9
	v_cvt_pk_bf16_f32 v235, v10, v11
	v_mul_f32_e32 v9, v9, v9
	s_nop 1
	v_permlane16_swap_b32_e32 v232, v234
	v_permlane16_swap_b32_e32 v233, v235
	v_lshl_add_u64 v[242:243], v[18:19], 0, v[240:241]
	global_store_dwordx4 v[242:243], v[232:235], off sc0 sc1
	v_mul_f32_e32 v11, v11, v11
	v_fmac_f32_e32 v9, v8, v8
	v_fmac_f32_e32 v11, v10, v10
	v_add_f32_e32 v8, v9, v11
	v_add_f32_e32 v8, v12, v8
	v_mov_b64_e32 v[22:23], v[226:227]
	v_lshlrev_b32_e32 v20, 16, v22
	v_and_b32_e32 v21, 0xffff0000, v22
	v_lshlrev_b32_e32 v22, 16, v23
	v_and_b32_e32 v23, 0xffff0000, v23
	v_pk_add_f32 v[6:7], v[6:7], v[22:23]
	v_pk_add_f32 v[4:5], v[4:5], v[20:21]
	s_nop 0
	v_cvt_pk_bf16_f32 v236, v4, v5
	v_cvt_pk_bf16_f32 v237, v6, v7
	v_mul_f32_e32 v5, v5, v5
	v_mul_f32_e32 v7, v7, v7
	v_fmac_f32_e32 v5, v4, v4
	v_fmac_f32_e32 v7, v6, v6
	v_add_f32_e32 v4, v5, v7
	v_add_f32_e32 v8, v8, v4
	s_nop 0
	v_mov_b64_e32 v[22:23], v[228:229]
	v_lshlrev_b32_e32 v4, 16, v22
	v_and_b32_e32 v5, 0xffff0000, v22
	v_lshlrev_b32_e32 v6, 16, v23
	v_and_b32_e32 v7, 0xffff0000, v23
	v_pk_add_f32 v[2:3], v[2:3], v[6:7]
	v_pk_add_f32 v[4:5], v[0:1], v[4:5]
	v_mul_f32_e32 v1, v3, v3
	v_mul_f32_e32 v0, v5, v5
	v_fmac_f32_e32 v0, v4, v4
	v_fmac_f32_e32 v1, v2, v2
	v_add_f32_e32 v0, v0, v1
	v_add_f32_e32 v0, v8, v0
	ds_bpermute_b32 v1, v149, v0
	v_cvt_pk_bf16_f32 v238, v4, v5
	v_cvt_pk_bf16_f32 v239, v2, v3
	s_nop 1
	v_permlane16_swap_b32_e32 v236, v238
	v_permlane16_swap_b32_e32 v237, v239
	v_lshl_add_u64 v[242:243], v[18:19], 0, v[240:241]
	global_store_dwordx4 v[242:243], v[236:239], off offset:256 sc0 sc1
	s_waitcnt lgkmcnt(0)
	v_add_f32_e32 v0, v0, v1
	ds_bpermute_b32 v1, v153, v0
	s_and_saveexec_b64 s[24:25], s[8:9]
	s_cbranch_execz .LBB0_1843
	s_waitcnt lgkmcnt(0)
	v_add_f32_e32 v2, v0, v1
	v_lshlrev_b64 v[0:1], 6, v[16:17]
	v_lshl_add_u64 v[0:1], s[60:61], 0, v[0:1]
	v_lshl_add_u64 v[0:1], s[22:23], 2, v[0:1]
	s_lshl_b32 s10, s40, 2
	v_lshl_add_u64 v[0:1], v[0:1], 0, s[10:11]
	global_store_dword v[0:1], v2, off
